# v_rm_m1 + pool phase (window variant 1): three chained row loads issued together instead of load-wait-load-wait
# baseline (speedup 1.0000x reference)
.LBB0_317:
	s_or_b32 s43, s18, 30
	s_or_b32 s38, s18, 31
	s_add_u32 s6, s43, s4
	s_addc_u32 s7, 0, s5
	s_add_i32 s8, s18, 45
	s_add_u32 s9, s38, s4
	s_addc_u32 s10, 0, s5
	s_add_i32 s11, s18, 46
	s_ashr_i32 s12, s11, 31
	s_cmp_gt_i32 s52, -1
	s_cselect_b32 s85, s10, s12
	s_cselect_b32 s84, s9, s11
	s_ashr_i32 s9, s8, 31
	s_cmp_gt_i32 s52, -1
	s_cselect_b32 s7, s7, s9
	s_cselect_b32 s6, s6, s8
	s_or_b32 s42, s18, 29
	s_add_u32 s8, s42, s4
	s_addc_u32 s9, 0, s5
	s_add_i32 s10, s18, 44
	s_ashr_i32 s11, s10, 31
	s_cmp_gt_i32 s52, -1
	s_cselect_b32 s9, s9, s11
	s_cselect_b32 s8, s8, s10
	s_or_b32 s46, s18, 28
	s_add_u32 s10, s46, s4
	s_addc_u32 s11, 0, s5
	s_add_i32 s12, s18, 43
	s_ashr_i32 s13, s12, 31
	s_cmp_gt_i32 s52, -1
	s_cselect_b32 s13, s11, s13
	s_cselect_b32 s12, s10, s12
	s_or_b32 s48, s18, 27
	s_add_u32 s10, s48, s4
	s_addc_u32 s11, 0, s5
	s_add_i32 s14, s18, 42
	s_ashr_i32 s15, s14, 31
	s_cmp_gt_i32 s52, -1
	s_cselect_b32 s15, s11, s15
	s_cselect_b32 s14, s10, s14
	s_or_b32 s50, s18, 26
	s_add_u32 s10, s50, s4
	s_addc_u32 s11, 0, s5
	s_add_i32 s16, s18, 41
	s_ashr_i32 s17, s16, 31
	s_cmp_gt_i32 s52, -1
	s_cselect_b32 s17, s11, s17
	s_cselect_b32 s16, s10, s16
	s_or_b32 s53, s18, 25
	s_add_u32 s10, s53, s4
	s_addc_u32 s11, 0, s5
	s_mov_b32 s86, s18
	s_add_i32 s18, s18, 40
	s_ashr_i32 s19, s18, 31
	s_cmp_gt_i32 s52, -1
	s_cselect_b32 s19, s11, s19
	s_cselect_b32 s18, s10, s18
	s_or_b32 s54, s86, 24
	s_add_u32 s10, s54, s4
	s_addc_u32 s11, 0, s5
	s_add_i32 s20, s86, 39
	s_ashr_i32 s21, s20, 31
	s_cmp_gt_i32 s52, -1
	s_cselect_b32 s21, s11, s21
	s_cselect_b32 s20, s10, s20
	s_or_b32 s66, s86, 23
	s_add_u32 s10, s66, s4
	s_addc_u32 s11, 0, s5
	s_add_i32 s22, s86, 38
	s_ashr_i32 s23, s22, 31
	s_cmp_gt_i32 s52, -1
	s_cselect_b32 s23, s11, s23
	s_cselect_b32 s22, s10, s22
	s_or_b32 s67, s86, 22
	s_add_u32 s10, s67, s4
	s_addc_u32 s11, 0, s5
	s_add_i32 s24, s86, 37
	s_ashr_i32 s25, s24, 31
	s_cmp_gt_i32 s52, -1
	s_cselect_b32 s25, s11, s25
	s_cselect_b32 s24, s10, s24
	s_or_b32 s72, s86, 21
	s_add_u32 s10, s72, s4
	s_addc_u32 s11, 0, s5
	s_add_i32 s26, s86, 36
	s_ashr_i32 s27, s26, 31
	s_cmp_gt_i32 s52, -1
	s_cselect_b32 s27, s11, s27
	s_cselect_b32 s26, s10, s26
	s_or_b32 s73, s86, 20
	s_add_u32 s10, s73, s4
	s_addc_u32 s11, 0, s5
	s_add_i32 s28, s86, 35
	s_ashr_i32 s29, s28, 31
	s_cmp_gt_i32 s52, -1
	s_cselect_b32 s29, s11, s29
	s_cselect_b32 s28, s10, s28
	s_or_b32 s74, s86, 19
	s_add_u32 s10, s74, s4
	s_addc_u32 s11, 0, s5
	s_add_i32 s30, s86, 34
	s_ashr_i32 s31, s30, 31
	s_cmp_gt_i32 s52, -1
	s_cselect_b32 s31, s11, s31
	s_cselect_b32 s30, s10, s30
	s_or_b32 s88, s86, 18
	s_add_u32 s10, s88, s4
	s_addc_u32 s11, 0, s5
	s_add_i32 s34, s86, 33
	s_ashr_i32 s35, s34, 31
	s_cmp_gt_i32 s52, -1
	s_cselect_b32 s35, s11, s35
	s_cselect_b32 s34, s10, s34
	s_or_b32 s89, s86, 17
	s_add_u32 s10, s89, s4
	s_addc_u32 s11, 0, s5
	s_add_i32 s36, s86, 32
	s_ashr_i32 s37, s36, 31
	s_cmp_gt_i32 s52, -1
	s_cselect_b32 s36, s10, s36
	s_cselect_b32 s37, s11, s37
	s_or_b32 vcc_lo, s86, 16
	s_add_u32 s10, vcc_lo, s4
	s_addc_u32 s11, 0, s5
	s_ashr_i32 s39, s38, 31
	v_writelane_b32 v254, s44, 57
	s_cmp_gt_i32 s52, -1
	v_writelane_b32 v254, s38, 48
	s_cselect_b32 s38, s10, s38
	s_cselect_b32 s39, s11, s39
	s_or_b32 s95, s86, 15
	s_add_u32 s10, s95, s4
	v_lshl_add_u64 v[76:77], s[40:41], 0, v[74:75]
	s_addc_u32 s11, 0, s5
	s_ashr_i32 s40, s43, 31
	s_cmp_gt_i32 s52, -1
	s_cselect_b32 s41, s11, s40
	s_cselect_b32 s40, s10, s43
	s_add_u32 s10, s44, s4
	s_addc_u32 s11, 0, s5
	s_mov_b32 s44, s42
	s_ashr_i32 s42, s42, 31
	v_writelane_b32 v254, s43, 49
	s_cmp_gt_i32 s52, -1
	v_writelane_b32 v254, s44, 50
	s_cselect_b32 s43, s11, s42
	s_cselect_b32 s42, s10, s44
	s_or_b32 s10, s86, 13
	v_writelane_b32 v254, s10, 59
	s_add_u32 s10, s10, s4
	s_addc_u32 s11, 0, s5
	s_ashr_i32 s44, s46, 31
	s_cmp_gt_i32 s52, -1
	v_writelane_b32 v254, s46, 52
	s_cselect_b32 s45, s11, s44
	s_cselect_b32 s44, s10, s46
	s_or_b32 s10, s86, 12
	v_writelane_b32 v254, s10, 61
	s_add_u32 s10, s10, s4
	s_addc_u32 s11, 0, s5
	s_ashr_i32 s46, s48, 31
	s_cmp_gt_i32 s52, -1
	v_writelane_b32 v254, s48, 54
	s_cselect_b32 s47, s11, s46
	s_cselect_b32 s46, s10, s48
	s_or_b32 s10, s86, 11
	v_writelane_b32 v254, s10, 63
	s_add_u32 s10, s10, s4
	s_addc_u32 s11, 0, s5
	s_ashr_i32 s48, s50, 31
	s_cmp_gt_i32 s52, -1
	s_cselect_b32 s49, s11, s48
	s_cselect_b32 s48, s10, s50
	s_or_b32 s10, s86, 10
	v_writelane_b32 v252, s10, 3
	s_add_u32 s10, s10, s4
	v_writelane_b32 v254, s50, 56
	s_addc_u32 s11, 0, s5
	s_ashr_i32 s50, s53, 31
	s_cmp_gt_i32 s52, -1
	s_cselect_b32 s51, s11, s50
	s_cselect_b32 s50, s10, s53
	s_or_b32 s10, s86, 9
	v_writelane_b32 v252, s10, 4
	s_add_u32 s10, s10, s4
	s_addc_u32 s11, 0, s5
	s_mov_b32 s94, s52
	s_ashr_i32 s52, s54, 31
	s_cmp_gt_i32 s94, -1
	v_writelane_b32 v254, s53, 58
	s_cselect_b32 s53, s11, s52
	s_cselect_b32 s52, s10, s54
	s_or_b32 s10, s86, 8
	v_writelane_b32 v252, s10, 5
	s_add_u32 s10, s10, s4
	v_writelane_b32 v254, s54, 60
	s_addc_u32 s11, 0, s5
	s_ashr_i32 s54, s66, 31
	s_cmp_gt_i32 s94, -1
	s_cselect_b32 s55, s11, s54
	s_cselect_b32 s54, s10, s66
	s_or_b32 s10, s86, 7
	v_writelane_b32 v252, s10, 9
	s_add_u32 s10, s10, s4
	v_writelane_b32 v254, s66, 62
	s_addc_u32 s11, 0, s5
	s_ashr_i32 s66, s67, 31
	s_cmp_gt_i32 s94, -1
	v_writelane_b32 v252, s67, 0
	s_cselect_b32 s81, s11, s66
	s_cselect_b32 s80, s10, s67
	s_or_b32 s10, s86, 6
	v_writelane_b32 v252, s10, 11
	s_add_u32 s10, s10, s4
	s_addc_u32 s11, 0, s5
	s_ashr_i32 s66, s72, 31
	s_cmp_gt_i32 s94, -1
	v_writelane_b32 v252, s72, 1
	s_cselect_b32 s79, s11, s66
	s_cselect_b32 s78, s10, s72
	s_or_b32 s10, s86, 5
	v_writelane_b32 v252, s10, 13
	s_add_u32 s10, s10, s4
	s_addc_u32 s11, 0, s5
	s_ashr_i32 s66, s73, 31
	s_cmp_gt_i32 s94, -1
	v_writelane_b32 v252, s73, 2
	s_cselect_b32 s91, s11, s66
	s_cselect_b32 s90, s10, s73
	s_or_b32 s10, s86, 4
	v_writelane_b32 v252, s10, 15
	s_add_u32 s10, s10, s4
	s_addc_u32 s11, 0, s5
	s_ashr_i32 s66, s74, 31
	s_cmp_gt_i32 s94, -1
	v_writelane_b32 v254, s74, 47
	s_cselect_b32 s75, s11, s66
	s_cselect_b32 s74, s10, s74
	s_or_b32 s10, s86, 3
	v_writelane_b32 v252, s10, 17
	s_add_u32 s10, s10, s4
	s_addc_u32 s11, 0, s5
	s_ashr_i32 s66, s88, 31
	s_cmp_gt_i32 s94, -1
	s_cselect_b32 s73, s11, s66
	s_cselect_b32 s72, s10, s88
	s_or_b32 s10, s86, 2
	v_writelane_b32 v252, s10, 18
	s_add_u32 s10, s10, s4
	s_addc_u32 s11, 0, s5
	s_ashr_i32 s66, s89, 31
	s_mov_b32 s67, s89
	s_cmp_gt_i32 s94, -1
	v_writelane_b32 v254, s88, 51
	s_cselect_b32 s89, s11, s66
	s_cselect_b32 s88, s10, s67
	s_or_b32 s10, s86, 1
	v_writelane_b32 v252, s10, 20
	s_add_u32 s10, s10, s4
	s_addc_u32 s11, 0, s5
	s_ashr_i32 s66, vcc_lo, 31
	s_cmp_gt_i32 s94, -1
	v_writelane_b32 v254, s67, 53
	s_cselect_b32 s11, s11, s66
	s_cselect_b32 s10, s10, vcc_lo
	v_writelane_b32 v252, s92, 7
	s_cselect_b32 s66, s96, s92
	s_cselect_b32 s67, s97, s93
	s_add_u32 s96, s86, s4
	v_writelane_b32 v254, vcc_lo, 55
	s_addc_u32 s97, 0, s5
	s_ashr_i32 vcc_lo, s95, 31
	s_cmp_gt_i32 s94, -1
	v_writelane_b32 v252, s93, 8
	s_cselect_b32 s97, s97, vcc_lo
	s_cselect_b32 s96, s96, s95
	s_lshl_b64 s[2:3], s[2:3], 11
	v_readlane_b32 s92, v254, 41
	s_cmp_lt_i32 s92, 1
	v_lshl_add_u64 v[134:135], v[76:77], 0, s[2:3]
	s_cselect_b64 vcc, -1, 0
	s_lshl_b64 s[2:3], s[96:97], 11
	v_lshl_add_u64 v[74:75], s[66:67], 0, v[74:75]
	s_cmp_lt_i32 s92, 0
	v_lshl_add_u64 v[136:137], v[74:75], 0, s[2:3]
	s_cselect_b64 s[66:67], -1, 0
	s_lshl_b64 s[2:3], s[10:11], 11
	s_cmp_lt_i32 s92, -1
	v_lshl_add_u64 v[138:139], v[74:75], 0, s[2:3]
	s_cselect_b64 s[2:3], -1, 0
	s_lshl_b64 s[10:11], s[88:89], 11
	s_cmp_lt_i32 s92, -2
	v_lshl_add_u64 v[140:141], v[74:75], 0, s[10:11]
	s_cselect_b64 s[88:89], -1, 0
	s_lshl_b64 s[10:11], s[72:73], 11
	s_cmp_lt_i32 s92, -3
	v_lshl_add_u64 v[142:143], v[74:75], 0, s[10:11]
	s_cselect_b64 s[72:73], -1, 0
	s_lshl_b64 s[10:11], s[74:75], 11
	s_cmp_lt_i32 s92, -4
	v_lshl_add_u64 v[144:145], v[74:75], 0, s[10:11]
	s_cselect_b64 s[74:75], -1, 0
	s_lshl_b64 s[10:11], s[90:91], 11
	s_cmp_lt_i32 s92, -5
	v_lshl_add_u64 v[146:147], v[74:75], 0, s[10:11]
	s_cselect_b64 s[90:91], -1, 0
	s_lshl_b64 s[10:11], s[78:79], 11
	s_cmp_lt_i32 s92, -6
	v_lshl_add_u64 v[148:149], v[74:75], 0, s[10:11]
	s_cselect_b64 s[78:79], -1, 0
	v_cndmask_b32_e64 v149, v149, v73, s[78:79]
	v_cndmask_b32_e64 v148, v148, v72, s[78:79]
	v_cndmask_b32_e64 v147, v147, v73, s[90:91]
	v_cndmask_b32_e64 v146, v146, v72, s[90:91]
	v_cndmask_b32_e64 v145, v145, v73, s[74:75]
	v_cndmask_b32_e64 v144, v144, v72, s[74:75]
	global_load_dwordx2 v[148:149], v[148:149], off
	v_cndmask_b32_e64 v143, v143, v73, s[72:73]
	global_load_dwordx2 v[146:147], v[146:147], off
	v_cndmask_b32_e64 v142, v142, v72, s[72:73]
	global_load_dwordx2 v[144:145], v[144:145], off
	v_cndmask_b32_e64 v141, v141, v73, s[88:89]
	v_cndmask_b32_e64 v140, v140, v72, s[88:89]
	v_cndmask_b32_e64 v139, v139, v73, s[2:3]
	v_cndmask_b32_e64 v138, v138, v72, s[2:3]
	v_cndmask_b32_e64 v137, v137, v73, s[66:67]
	v_cndmask_b32_e64 v136, v136, v72, s[66:67]
	v_cndmask_b32_e32 v135, v135, v73, vcc
	v_cndmask_b32_e32 v134, v134, v72, vcc
	s_lshl_b64 s[10:11], s[80:81], 11
	s_cmp_lt_i32 s92, -7
	v_lshl_add_u64 v[150:151], v[74:75], 0, s[10:11]
	s_cselect_b64 s[80:81], -1, 0
	s_lshl_b64 s[10:11], s[54:55], 11
	s_cmp_lt_i32 s92, -8
	v_lshl_add_u64 v[132:133], v[74:75], 0, s[10:11]
	s_cselect_b64 s[54:55], -1, 0
	s_lshl_b64 s[10:11], s[52:53], 11
	s_cmp_lt_i32 s92, -9
	v_lshl_add_u64 v[122:123], v[74:75], 0, s[10:11]
	s_cselect_b64 s[52:53], -1, 0
	s_lshl_b64 s[10:11], s[50:51], 11
	s_cmp_lt_i32 s92, -10
	v_lshl_add_u64 v[106:107], v[74:75], 0, s[10:11]
	s_cselect_b64 s[50:51], -1, 0
	s_lshl_b64 s[10:11], s[48:49], 11
	s_cmp_lt_i32 s92, -11
	v_lshl_add_u64 v[108:109], v[74:75], 0, s[10:11]
	s_cselect_b64 s[48:49], -1, 0
	s_lshl_b64 s[10:11], s[46:47], 11
	s_cmp_lt_i32 s92, -12
	v_lshl_add_u64 v[110:111], v[74:75], 0, s[10:11]
	s_cselect_b64 s[46:47], -1, 0
	s_lshl_b64 s[10:11], s[44:45], 11
	s_cmp_lt_i32 s92, -13
	v_lshl_add_u64 v[112:113], v[74:75], 0, s[10:11]
	s_cselect_b64 s[44:45], -1, 0
	s_lshl_b64 s[10:11], s[42:43], 11
	s_cmp_lt_i32 s92, -14
	v_lshl_add_u64 v[114:115], v[74:75], 0, s[10:11]
	s_cselect_b64 s[42:43], -1, 0
	s_lshl_b64 s[10:11], s[40:41], 11
	s_cmp_lt_i32 s92, -15
	v_lshl_add_u64 v[118:119], v[74:75], 0, s[10:11]
	s_cselect_b64 s[40:41], -1, 0
	s_lshl_b64 s[10:11], s[38:39], 11
	s_cmp_lt_i32 s92, -16
	v_lshl_add_u64 v[104:105], v[74:75], 0, s[10:11]
	s_cselect_b64 s[38:39], -1, 0
	s_lshl_b64 s[10:11], s[36:37], 11
	s_cmpk_lt_i32 s92, 0xffef
	v_lshl_add_u64 v[102:103], v[74:75], 0, s[10:11]
	s_cselect_b64 s[36:37], -1, 0
	s_lshl_b64 s[10:11], s[34:35], 11
	s_cmpk_lt_i32 s92, 0xffee
	v_lshl_add_u64 v[100:101], v[74:75], 0, s[10:11]
	s_cselect_b64 s[34:35], -1, 0
	s_lshl_b64 s[10:11], s[30:31], 11
	s_cmpk_lt_i32 s92, 0xffed
	v_lshl_add_u64 v[98:99], v[74:75], 0, s[10:11]
	s_cselect_b64 s[30:31], -1, 0
	s_lshl_b64 s[10:11], s[28:29], 11
	s_cmpk_lt_i32 s92, 0xffec
	v_lshl_add_u64 v[96:97], v[74:75], 0, s[10:11]
	s_cselect_b64 s[28:29], -1, 0
	s_lshl_b64 s[10:11], s[26:27], 11
	s_cmpk_lt_i32 s92, 0xffeb
	v_lshl_add_u64 v[94:95], v[74:75], 0, s[10:11]
	s_cselect_b64 s[26:27], -1, 0
	s_lshl_b64 s[10:11], s[24:25], 11
	s_cmpk_lt_i32 s92, 0xffea
	v_lshl_add_u64 v[92:93], v[74:75], 0, s[10:11]
	s_cselect_b64 s[24:25], -1, 0
	s_lshl_b64 s[10:11], s[22:23], 11
	s_cmpk_lt_i32 s92, 0xffe9
	v_lshl_add_u64 v[90:91], v[74:75], 0, s[10:11]
	s_waitcnt vmcnt(2)
	v_cndmask_b32_e64 v157, v149, 0, s[78:79]
	s_cselect_b64 s[22:23], -1, 0
	s_waitcnt vmcnt(1)
	v_cndmask_b32_e64 v159, v147, 0, s[90:91]
	s_lshl_b64 s[10:11], s[20:21], 11
	s_waitcnt vmcnt(0)
	v_cndmask_b32_e64 v149, v145, 0, s[74:75]
	v_cndmask_b32_e64 v147, v144, 0, s[74:75]
	global_load_dwordx2 v[144:145], v[142:143], off
	s_cmpk_lt_i32 s92, 0xffe8
	v_lshl_add_u64 v[88:89], v[74:75], 0, s[10:11]
	s_cselect_b64 s[20:21], -1, 0
	s_lshl_b64 s[10:11], s[18:19], 11
	s_cmpk_lt_i32 s92, 0xffe7
	v_lshl_add_u64 v[86:87], v[74:75], 0, s[10:11]
	s_cselect_b64 s[18:19], -1, 0
	s_lshl_b64 s[10:11], s[16:17], 11
	s_cmpk_lt_i32 s92, 0xffe6
	v_lshl_add_u64 v[84:85], v[74:75], 0, s[10:11]
	s_cselect_b64 s[16:17], -1, 0
	s_lshl_b64 s[10:11], s[14:15], 11
	s_cmpk_lt_i32 s92, 0xffe5
	v_lshl_add_u64 v[82:83], v[74:75], 0, s[10:11]
	s_cselect_b64 s[14:15], -1, 0
	s_lshl_b64 s[10:11], s[12:13], 11
	s_cmpk_lt_i32 s92, 0xffe4
	s_cselect_b64 s[12:13], -1, 0
	s_lshl_b64 s[8:9], s[8:9], 11
	s_cmpk_lt_i32 s92, 0xffe3
	v_lshl_add_u64 v[78:79], v[74:75], 0, s[8:9]
	s_cselect_b64 s[8:9], -1, 0
	s_lshl_b64 s[6:7], s[6:7], 11
	s_cmpk_lt_i32 s92, 0xffe2
	v_lshl_add_u64 v[80:81], v[74:75], 0, s[10:11]
	v_lshl_add_u64 v[76:77], v[74:75], 0, s[6:7]
	s_cselect_b64 s[6:7], -1, 0
	s_lshl_b64 s[10:11], s[84:85], 11
	s_cmpk_lt_i32 s92, 0xffe1
	v_lshl_add_u64 v[74:75], v[74:75], 0, s[10:11]
	s_cselect_b64 s[10:11], -1, 0
	v_cndmask_b32_e64 v166, v116, 0, s[82:83]
	v_cndmask_b32_e64 v165, v117, 0, s[82:83]
	v_cndmask_b32_e64 v158, v148, 0, s[78:79]
	v_cndmask_b32_e64 v148, v120, 0, s[56:57]
	v_cndmask_b32_e64 v161, v146, 0, s[90:91]
	v_cndmask_b32_e64 v146, v121, 0, s[56:57]
	v_cndmask_b32_e64 v151, v151, v73, s[80:81]
	v_cndmask_b32_e64 v150, v150, v72, s[80:81]
	global_load_dwordx2 v[150:151], v[150:151], off
	v_lshlrev_b32_e32 v184, 3, v153
	v_and_b32_e32 v179, 0x1f0, v184
	v_bitop3_b32 v175, v184, 16, v240 bitop3:0x6c
	v_bitop3_b32 v170, v184, 32, v240 bitop3:0x6c
	v_bitop3_b32 v167, v184, 48, v240 bitop3:0x6c
	v_bitop3_b32 v164, v184, 64, v240 bitop3:0x6c
	v_bitop3_b32 v155, v184, s33, v240 bitop3:0x6c
	v_cndmask_b32_e64 v107, v107, v73, s[50:51]
	v_cndmask_b32_e64 v106, v106, v72, s[50:51]
	v_cndmask_b32_e64 v125, v125, 0, s[58:59]
	v_cndmask_b32_e64 v124, v124, 0, s[58:59]
	v_lshlrev_b32_e32 v194, 16, v148
	v_and_b32_e32 v195, 0xffff0000, v148
	v_lshlrev_b32_e32 v196, 16, v146
	v_and_b32_e32 v197, 0xffff0000, v146
	v_cndmask_b32_e64 v127, v127, 0, s[60:61]
	v_cndmask_b32_e64 v126, v126, 0, s[60:61]
	v_cndmask_b32_e64 v129, v129, 0, s[62:63]
	v_cndmask_b32_e64 v128, v128, 0, s[62:63]
	v_lshlrev_b32_e32 v198, 16, v126
	v_and_b32_e32 v199, 0xffff0000, v126
	v_lshlrev_b32_e32 v126, 16, v127
	v_and_b32_e32 v127, 0xffff0000, v127
	v_cndmask_b32_e64 v131, v131, 0, s[64:65]
	v_cndmask_b32_e64 v130, v130, 0, s[64:65]
	v_lshlrev_b32_e32 v200, 16, v130
	v_and_b32_e32 v201, 0xffff0000, v130
	v_lshlrev_b32_e32 v130, 16, v131
	v_and_b32_e32 v131, 0xffff0000, v131
	v_lshlrev_b32_e32 v148, 16, v149
	v_and_b32_e32 v149, 0xffff0000, v149
	v_cndmask_b32_e64 v105, v105, v73, s[38:39]
	v_cndmask_b32_e64 v104, v104, v72, s[38:39]
	global_load_dwordx2 v[104:105], v[104:105], off
	v_cndmask_b32_e64 v103, v103, v73, s[36:37]
	v_cndmask_b32_e64 v102, v102, v72, s[36:37]
	global_load_dwordx2 v[102:103], v[102:103], off
	v_cndmask_b32_e64 v101, v101, v73, s[34:35]
	v_cndmask_b32_e64 v100, v100, v72, s[34:35]
	s_waitcnt vmcnt(3)
	v_cndmask_b32_e64 v142, v145, 0, s[72:73]
	v_cndmask_b32_e64 v143, v144, 0, s[72:73]
	global_load_dwordx2 v[144:145], v[140:141], off
	v_cndmask_b32_e64 v99, v99, v73, s[30:31]
	global_load_dwordx2 v[100:101], v[100:101], off
	v_cndmask_b32_e64 v98, v98, v72, s[30:31]
	global_load_dwordx2 v[98:99], v[98:99], off
	v_cndmask_b32_e64 v97, v97, v73, s[28:29]
	v_cndmask_b32_e64 v96, v96, v72, s[28:29]
	global_load_dwordx2 v[96:97], v[96:97], off
	v_cndmask_b32_e64 v95, v95, v73, s[26:27]
	v_cndmask_b32_e64 v94, v94, v72, s[26:27]
	global_load_dwordx2 v[94:95], v[94:95], off
	v_cndmask_b32_e64 v93, v93, v73, s[24:25]
	v_cndmask_b32_e64 v92, v92, v72, s[24:25]
	global_load_dwordx2 v[92:93], v[92:93], off
	v_cndmask_b32_e64 v91, v91, v73, s[22:23]
	v_cndmask_b32_e64 v90, v90, v72, s[22:23]
	global_load_dwordx2 v[90:91], v[90:91], off
	v_cndmask_b32_e64 v89, v89, v73, s[20:21]
	v_cndmask_b32_e64 v88, v88, v72, s[20:21]
	global_load_dwordx2 v[88:89], v[88:89], off
	v_cndmask_b32_e64 v87, v87, v73, s[18:19]
	v_cndmask_b32_e64 v86, v86, v72, s[18:19]
	global_load_dwordx2 v[86:87], v[86:87], off
	v_cndmask_b32_e64 v85, v85, v73, s[16:17]
	v_cndmask_b32_e64 v84, v84, v72, s[16:17]
	global_load_dwordx2 v[84:85], v[84:85], off
	v_cndmask_b32_e64 v83, v83, v73, s[14:15]
	v_cndmask_b32_e64 v82, v82, v72, s[14:15]
	global_load_dwordx2 v[82:83], v[82:83], off
	v_cndmask_b32_e64 v81, v81, v73, s[12:13]
	v_cndmask_b32_e64 v80, v80, v72, s[12:13]
	global_load_dwordx2 v[80:81], v[80:81], off
	v_cndmask_b32_e64 v77, v77, v73, s[6:7]
	v_cndmask_b32_e64 v76, v76, v72, s[6:7]
	global_load_dwordx2 v[76:77], v[76:77], off
	v_readlane_b32 s78, v254, 44
	v_readlane_b32 s96, v254, 39
	v_readlane_b32 s74, v254, 42
	s_waitcnt vmcnt(15)
	v_cndmask_b32_e64 v156, v150, 0, s[80:81]
	v_and_b32_e32 v150, 8, v184
	v_cndmask_b32_e64 v151, v151, 0, s[80:81]
	v_readlane_b32 s79, v254, 45
	v_readlane_b32 s97, v254, 40
	s_mov_b64 s[82:83], 0
	v_readlane_b32 s85, v254, 8
	v_readlane_b32 s93, v254, 10
	v_readlane_b32 s75, v254, 43
	v_readlane_b32 s80, v254, 15
	v_readlane_b32 s81, v254, 22
	v_readlane_b32 s84, v254, 23
	v_readlane_b32 s79, v254, 24
	s_mov_b32 s72, 0x40000
	s_waitcnt vmcnt(12)
	v_cndmask_b32_e64 v140, v145, 0, s[88:89]
	v_cndmask_b32_e64 v141, v144, 0, s[88:89]
	global_load_dwordx2 v[144:145], v[138:139], off
	global_load_dwordx2 v[188:189], v[136:137], off
	global_load_dwordx2 v[190:191], v[134:135], off
	v_readlane_b32 s89, v254, 14
	s_movk_i32 s88, 0x1000
	s_waitcnt vmcnt(10)
	v_cndmask_b32_e64 v93, v93, 0, s[24:25]
	s_waitcnt vmcnt(8)
	v_cndmask_b32_e64 v89, v89, 0, s[20:21]
	s_waitcnt vmcnt(7)
	v_cndmask_b32_e64 v87, v87, 0, s[18:19]
	s_waitcnt vmcnt(6)
	v_cndmask_b32_e64 v85, v85, 0, s[16:17]
	s_waitcnt vmcnt(5)
	v_cndmask_b32_e64 v83, v83, 0, s[14:15]
	s_waitcnt vmcnt(4)
	v_cndmask_b32_e64 v81, v81, 0, s[12:13]
	s_waitcnt vmcnt(3)
	v_cndmask_b32_e64 v77, v77, 0, s[6:7]
	s_waitcnt vmcnt(2)
	v_cndmask_b32_e64 v138, v145, 0, s[2:3]
	v_cndmask_b32_e64 v139, v144, 0, s[2:3]
	s_min_i32 s2, s92, 7
	s_add_i32 s2, s2, 1
	v_cvt_f32_i32_e32 v168, s2
	v_div_scale_f32 v71, s[2:3], v168, v168, 1.0
	v_rcp_f32_e32 v116, v71
	s_min_i32 s2, s92, 6
	s_add_i32 s2, s2, 2
	v_cvt_f32_i32_e32 v171, s2
	v_fma_f32 v117, -v71, v116, 1.0
	v_fmac_f32_e32 v116, v117, v116
	s_waitcnt vmcnt(1)
	v_cndmask_b32_e64 v136, v189, 0, s[66:67]
	v_cndmask_b32_e64 v137, v188, 0, s[66:67]
	v_lshlrev_b32_e32 v204, 16, v136
	v_and_b32_e32 v205, 0xffff0000, v136
	s_waitcnt vmcnt(0)
	v_cndmask_b32_e64 v134, v191, 0, vcc
	v_cndmask_b32_e64 v135, v190, 0, vcc
	v_div_scale_f32 v117, vcc, 1.0, v168, 1.0
	v_mul_f32_e32 v120, v117, v116
	v_fma_f32 v121, -v71, v120, v117
	v_fmac_f32_e32 v120, v121, v116
	v_fma_f32 v71, -v71, v120, v117
	v_div_fmas_f32 v169, v71, v116, v120
	v_div_scale_f32 v71, s[2:3], v171, v171, 1.0
	v_rcp_f32_e32 v116, v71
	s_min_i32 s2, s92, 5
	s_add_i32 s2, s2, 3
	v_cvt_f32_i32_e32 v173, s2
	v_fma_f32 v117, -v71, v116, 1.0
	v_fmac_f32_e32 v116, v117, v116
	v_div_scale_f32 v117, vcc, 1.0, v171, 1.0
	v_mul_f32_e32 v120, v117, v116
	v_fma_f32 v121, -v71, v120, v117
	v_fmac_f32_e32 v120, v121, v116
	v_fma_f32 v71, -v71, v120, v117
	v_div_fmas_f32 v172, v71, v116, v120
	v_div_scale_f32 v71, s[2:3], v173, v173, 1.0
	v_rcp_f32_e32 v116, v71
	s_min_i32 s2, s92, 4
	s_add_i32 s2, s2, 4
	v_cvt_f32_i32_e32 v176, s2
	v_fma_f32 v117, -v71, v116, 1.0
	v_fmac_f32_e32 v116, v117, v116
	v_div_scale_f32 v117, vcc, 1.0, v173, 1.0
	v_mul_f32_e32 v120, v117, v116
	v_fma_f32 v121, -v71, v120, v117
	v_fmac_f32_e32 v120, v121, v116
	v_fma_f32 v71, -v71, v120, v117
	v_div_fmas_f32 v174, v71, v116, v120
	v_div_scale_f32 v71, s[2:3], v176, v176, 1.0
	v_rcp_f32_e32 v116, v71
	s_min_i32 s2, s92, 3
	s_add_i32 s2, s2, 5
	v_cvt_f32_i32_e32 v178, s2
	v_fma_f32 v117, -v71, v116, 1.0
	v_fmac_f32_e32 v116, v117, v116
	v_div_scale_f32 v117, vcc, 1.0, v176, 1.0
	v_mul_f32_e32 v120, v117, v116
	v_fma_f32 v121, -v71, v120, v117
	v_fmac_f32_e32 v120, v121, v116
	v_fma_f32 v71, -v71, v120, v117
	v_div_fmas_f32 v177, v71, v116, v120
	v_div_scale_f32 v71, s[2:3], v178, v178, 1.0
	v_rcp_f32_e32 v116, v71
	s_min_i32 s2, s92, 2
	s_add_i32 s2, s2, 6
	v_cvt_f32_i32_e32 v181, s2
	v_fma_f32 v117, -v71, v116, 1.0
	v_fmac_f32_e32 v116, v117, v116
	v_div_scale_f32 v117, vcc, 1.0, v178, 1.0
	v_mul_f32_e32 v120, v117, v116
	v_fma_f32 v121, -v71, v120, v117
	v_fmac_f32_e32 v120, v121, v116
	v_fma_f32 v71, -v71, v120, v117
	v_div_fmas_f32 v180, v71, v116, v120
	v_div_scale_f32 v71, s[2:3], v181, v181, 1.0
	v_rcp_f32_e32 v116, v71
	s_min_i32 s2, s92, 1
	s_add_i32 s2, s2, 7
	v_cvt_f32_i32_e32 v183, s2
	v_fma_f32 v117, -v71, v116, 1.0
	v_fmac_f32_e32 v116, v117, v116
	v_div_scale_f32 v117, vcc, 1.0, v181, 1.0
	v_mul_f32_e32 v120, v117, v116
	v_fma_f32 v121, -v71, v120, v117
	v_fmac_f32_e32 v120, v121, v116
	v_fma_f32 v71, -v71, v120, v117
	v_div_fmas_f32 v182, v71, v116, v120
	v_div_scale_f32 v71, s[2:3], v183, v183, 1.0
	v_rcp_f32_e32 v116, v71
	s_min_i32 s2, s92, 0
	s_or_b32 s2, s2, 8
	v_cvt_f32_i32_e32 v186, s2
	v_fma_f32 v117, -v71, v116, 1.0
	v_fmac_f32_e32 v116, v117, v116
	v_div_scale_f32 v117, vcc, 1.0, v183, 1.0
	v_mul_f32_e32 v120, v117, v116
	v_fma_f32 v121, -v71, v120, v117
	v_fmac_f32_e32 v120, v121, v116
	v_fma_f32 v71, -v71, v120, v117
	v_div_fmas_f32 v185, v71, v116, v120
	v_div_scale_f32 v71, s[2:3], v186, v186, 1.0
	v_rcp_f32_e32 v116, v71
	s_min_i32 s2, s92, -1
	s_add_i32 s2, s2, 9
	v_cvt_f32_i32_e32 v210, s2
	v_fma_f32 v117, -v71, v116, 1.0
	v_fmac_f32_e32 v116, v117, v116
	v_div_scale_f32 v117, vcc, 1.0, v186, 1.0
	v_mul_f32_e32 v120, v117, v116
	v_fma_f32 v121, -v71, v120, v117
	v_fmac_f32_e32 v120, v121, v116
	v_fma_f32 v71, -v71, v120, v117
	v_div_fmas_f32 v187, v71, v116, v120
	v_cndmask_b32_e64 v117, v133, v73, s[54:55]
	v_cndmask_b32_e64 v116, v132, v72, s[54:55]
	global_load_dwordx2 v[116:117], v[116:117], off
	v_div_scale_f32 v71, s[2:3], v210, v210, 1.0
	s_min_i32 s2, s92, -2
	s_add_i32 s2, s2, 10
	v_cvt_f32_i32_e32 v214, s2
	global_load_dwordx2 v[144:145], v[106:107], off
	v_cndmask_b32_e64 v107, v109, v73, s[48:49]
	v_cndmask_b32_e64 v106, v108, v72, s[48:49]
	v_lshlrev_b32_e32 v202, 16, v134
	v_and_b32_e32 v203, 0xffff0000, v134
	s_waitcnt vmcnt(1)
	v_cndmask_b32_e64 v209, v116, 0, s[54:55]
	v_rcp_f32_e32 v116, v71
	v_cndmask_b32_e64 v208, v117, 0, s[54:55]
	v_fma_f32 v117, -v71, v116, 1.0
	v_fmac_f32_e32 v116, v117, v116
	v_div_scale_f32 v117, vcc, 1.0, v210, 1.0
	v_mul_f32_e32 v120, v117, v116
	v_fma_f32 v121, -v71, v120, v117
	v_fmac_f32_e32 v120, v121, v116
	v_fma_f32 v71, -v71, v120, v117
	v_div_fmas_f32 v211, v71, v116, v120
	v_cndmask_b32_e64 v117, v123, v73, s[52:53]
	v_cndmask_b32_e64 v116, v122, v72, s[52:53]
	global_load_dwordx2 v[116:117], v[116:117], off
	v_div_scale_f32 v71, s[2:3], v214, v214, 1.0
	s_lshl_b32 s2, s94, 14
	s_add_i32 s2, s2, 0
	v_add3_u32 v216, s2, v179, v150
	v_readlane_b32 s2, v252, 20
	s_lshl_b32 s2, s2, 9
	s_add_i32 s2, s2, 0
	v_add3_u32 v217, s2, v175, v150
	v_readlane_b32 s2, v252, 18
	s_lshl_b32 s2, s2, 9
	s_add_i32 s2, s2, 0
	v_add3_u32 v218, s2, v170, v150
	v_readlane_b32 s2, v252, 17
	s_lshl_b32 s2, s2, 9
	s_add_i32 s2, s2, 0
	v_add3_u32 v219, s2, v167, v150
	v_readlane_b32 s2, v252, 15
	s_lshl_b32 s2, s2, 9
	s_add_i32 s2, s2, 0
	v_add3_u32 v220, s2, v164, v150
	v_readlane_b32 s2, v252, 13
	s_lshl_b32 s2, s2, 9
	s_movk_i32 s3, 0x50
	s_add_i32 s2, s2, 0
	v_bitop3_b32 v163, v184, s3, v240 bitop3:0x6c
	v_add3_u32 v221, s2, v163, v150
	v_readlane_b32 s2, v252, 11
	s_lshl_b32 s2, s2, 9
	s_movk_i32 s3, 0x60
	s_add_i32 s2, s2, 0
	v_bitop3_b32 v162, v184, s3, v240 bitop3:0x6c
	v_add3_u32 v222, s2, v162, v150
	v_readlane_b32 s2, v252, 9
	s_lshl_b32 s2, s2, 9
	s_movk_i32 s3, 0x70
	s_add_i32 s2, s2, 0
	v_bitop3_b32 v160, v184, s3, v240 bitop3:0x6c
	v_add3_u32 v223, s2, v160, v150
	v_readlane_b32 s2, v252, 5
	s_lshl_b32 s2, s2, 9
	s_add_i32 s2, s2, 0
	v_add3_u32 v224, s2, v155, v150
	v_readlane_b32 s2, v254, 38
	global_load_dwordx2 v[122:123], v[106:107], off
	v_cndmask_b32_e64 v107, v111, v73, s[46:47]
	v_cndmask_b32_e64 v106, v110, v72, s[46:47]
	s_movk_i32 s3, 0x90
	s_waitcnt vmcnt(1)
	v_cndmask_b32_e64 v213, v116, 0, s[52:53]
	v_rcp_f32_e32 v116, v71
	v_cndmask_b32_e64 v212, v117, 0, s[52:53]
	s_mov_b32 s52, s94
	v_readlane_b32 s94, v254, 11
	v_fma_f32 v117, -v71, v116, 1.0
	v_fmac_f32_e32 v116, v117, v116
	v_div_scale_f32 v117, vcc, 1.0, v214, 1.0
	v_mul_f32_e32 v120, v117, v116
	v_fma_f32 v121, -v71, v120, v117
	v_fmac_f32_e32 v120, v121, v116
	v_fma_f32 v71, -v71, v120, v117
	v_div_fmas_f32 v215, v71, v116, v120
	v_mov_b32_e32 v71, s2
	global_load_dwordx2 v[116:117], v[106:107], off
	v_cndmask_b32_e64 v107, v113, v73, s[44:45]
	v_cndmask_b32_e64 v106, v112, v72, s[44:45]
	ds_read_b128 v[110:113], v71 offset:32
	ds_read_b128 v[188:191], v71 offset:48
	global_load_dwordx2 v[120:121], v[106:107], off
	v_cndmask_b32_e64 v107, v115, v73, s[42:43]
	v_cndmask_b32_e64 v106, v114, v72, s[42:43]
	global_load_dwordx2 v[108:109], v[106:107], off
	v_cndmask_b32_e64 v107, v119, v73, s[40:41]
	v_cndmask_b32_e64 v106, v118, v72, s[40:41]
	v_lshlrev_b32_e32 v114, 16, v166
	v_and_b32_e32 v115, 0xffff0000, v166
	v_lshlrev_b32_e32 v118, 16, v165
	v_and_b32_e32 v119, 0xffff0000, v165
	s_waitcnt lgkmcnt(1)
	v_pk_fma_f32 v[132:133], v[110:111], v[118:119], 0 op_sel_hi:[0,1,0]
	v_pk_fma_f32 v[192:193], v[110:111], v[114:115], 0 op_sel_hi:[0,1,0]
	v_pk_fma_f32 v[192:193], v[110:111], v[194:195], v[192:193] op_sel:[1,0,0]
	v_pk_fma_f32 v[110:111], v[110:111], v[196:197], v[132:133] op_sel:[1,0,0]
	v_lshlrev_b32_e32 v132, 16, v124
	v_and_b32_e32 v133, 0xffff0000, v124
	v_lshlrev_b32_e32 v124, 16, v125
	v_and_b32_e32 v125, 0xffff0000, v125
	v_pk_fma_f32 v[110:111], v[112:113], v[124:125], v[110:111] op_sel_hi:[0,1,1]
	v_pk_fma_f32 v[192:193], v[112:113], v[132:133], v[192:193] op_sel_hi:[0,1,1]
	v_mov_b32_e32 v112, v113
	v_pk_fma_f32 v[192:193], v[112:113], v[198:199], v[192:193] op_sel_hi:[0,1,1]
	v_pk_fma_f32 v[110:111], v[112:113], v[126:127], v[110:111] op_sel_hi:[0,1,1]
	v_lshlrev_b32_e32 v112, 16, v128
	v_and_b32_e32 v113, 0xffff0000, v128
	v_lshlrev_b32_e32 v128, 16, v129
	v_and_b32_e32 v129, 0xffff0000, v129
	s_waitcnt lgkmcnt(0)
	v_pk_fma_f32 v[110:111], v[188:189], v[128:129], v[110:111] op_sel_hi:[0,1,1]
	v_pk_fma_f32 v[192:193], v[188:189], v[112:113], v[192:193] op_sel_hi:[0,1,1]
	v_pk_fma_f32 v[192:193], v[188:189], v[200:201], v[192:193] op_sel:[1,0,0]
	v_pk_fma_f32 v[110:111], v[188:189], v[130:131], v[110:111] op_sel:[1,0,0]
	v_lshlrev_b32_e32 v188, 16, v135
	v_and_b32_e32 v189, 0xffff0000, v135
	v_pk_fma_f32 v[110:111], v[190:191], v[202:203], v[110:111] op_sel_hi:[0,1,1]
	v_pk_fma_f32 v[134:135], v[190:191], v[188:189], v[192:193] op_sel_hi:[0,1,1]
	v_lshlrev_b32_e32 v192, 16, v137
	v_and_b32_e32 v193, 0xffff0000, v137
	v_mov_b32_e32 v136, v191
	v_pk_mul_f32 v[190:191], v[136:137], v[192:193] op_sel_hi:[0,1]
	v_pk_mul_f32 v[206:207], v[136:137], v[204:205] op_sel_hi:[0,1]
	v_pk_fma_f32 v[134:135], v[136:137], v[192:193], v[134:135] op_sel_hi:[0,1,1]
	v_pk_fma_f32 v[110:111], v[136:137], v[204:205], v[110:111] op_sel_hi:[0,1,1]
	v_div_fixup_f32 v136, v169, v168, 1.0
	v_pk_fma_f32 v[168:169], v[136:137], v[110:111], v[206:207] op_sel_hi:[0,1,1] neg_lo:[0,0,1] neg_hi:[0,0,1]
	v_pk_fma_f32 v[136:137], v[136:137], v[134:135], v[190:191] op_sel_hi:[0,1,1] neg_lo:[0,0,1] neg_hi:[0,0,1]
	v_cvt_pk_bf16_f32 v136, v136, v137
	v_cvt_pk_bf16_f32 v137, v168, v169
	ds_write_b64 v216, v[136:137]
	ds_read_b32 v136, v71 offset:32
	ds_read_b32 v146, v71 offset:64
	v_lshlrev_b32_e32 v168, 16, v138
	v_and_b32_e32 v169, 0xffff0000, v138
	v_div_fixup_f32 v138, v172, v171, 1.0
	s_waitcnt lgkmcnt(1)
	v_pk_fma_f32 v[110:111], v[136:137], v[118:119], v[110:111] op_sel_hi:[0,1,1] neg_lo:[1,0,0] neg_hi:[1,0,0]
	v_pk_fma_f32 v[114:115], v[136:137], v[114:115], v[134:135] op_sel_hi:[0,1,1] neg_lo:[1,0,0] neg_hi:[1,0,0]
	v_lshlrev_b32_e32 v118, 16, v139
	v_and_b32_e32 v119, 0xffff0000, v139
	s_waitcnt lgkmcnt(0)
	v_pk_mul_f32 v[134:135], v[146:147], v[118:119] op_sel_hi:[0,1]
	v_pk_fma_f32 v[114:115], v[146:147], v[118:119], v[114:115] op_sel_hi:[0,1,1]
	v_pk_mul_f32 v[136:137], v[146:147], v[168:169] op_sel_hi:[0,1]
	v_pk_fma_f32 v[110:111], v[146:147], v[168:169], v[110:111] op_sel_hi:[0,1,1]
	v_pk_fma_f32 v[134:135], v[138:139], v[114:115], v[134:135] op_sel_hi:[0,1,1] neg_lo:[0,0,1] neg_hi:[0,0,1]
	v_pk_fma_f32 v[136:137], v[138:139], v[110:111], v[136:137] op_sel_hi:[0,1,1] neg_lo:[0,0,1] neg_hi:[0,0,1]
	v_cvt_pk_bf16_f32 v134, v134, v135
	v_cvt_pk_bf16_f32 v135, v136, v137
	ds_write_b64 v217, v[134:135]
	ds_read_b32 v134, v71 offset:36
	ds_read_b32 v136, v71 offset:68
	v_lshlrev_b32_e32 v190, 16, v141
	v_and_b32_e32 v191, 0xffff0000, v141
	v_lshlrev_b32_e32 v172, 16, v143
	s_waitcnt lgkmcnt(1)
	v_pk_fma_f32 v[110:111], v[134:135], v[196:197], v[110:111] op_sel_hi:[0,1,1] neg_lo:[1,0,0] neg_hi:[1,0,0]
	v_pk_fma_f32 v[114:115], v[134:135], v[194:195], v[114:115] op_sel_hi:[0,1,1] neg_lo:[1,0,0] neg_hi:[1,0,0]
	v_lshlrev_b32_e32 v194, 16, v140
	v_and_b32_e32 v195, 0xffff0000, v140
	s_waitcnt lgkmcnt(0)
	v_pk_mul_f32 v[134:135], v[136:137], v[190:191] op_sel_hi:[0,1]
	v_pk_mul_f32 v[138:139], v[136:137], v[194:195] op_sel_hi:[0,1]
	v_pk_fma_f32 v[114:115], v[136:137], v[190:191], v[114:115] op_sel_hi:[0,1,1]
	v_pk_fma_f32 v[110:111], v[136:137], v[194:195], v[110:111] op_sel_hi:[0,1,1]
	v_div_fixup_f32 v136, v174, v173, 1.0
	v_pk_fma_f32 v[134:135], v[136:137], v[114:115], v[134:135] op_sel_hi:[0,1,1] neg_lo:[0,0,1] neg_hi:[0,0,1]
	v_pk_fma_f32 v[138:139], v[136:137], v[110:111], v[138:139] op_sel_hi:[0,1,1] neg_lo:[0,0,1] neg_hi:[0,0,1]
	v_cvt_pk_bf16_f32 v134, v134, v135
	v_cvt_pk_bf16_f32 v135, v138, v139
	ds_write_b64 v218, v[134:135]
	ds_read_b32 v134, v71 offset:40
	ds_read_b32 v136, v71 offset:72
	v_and_b32_e32 v173, 0xffff0000, v143
	v_lshlrev_b32_e32 v196, 16, v142
	v_and_b32_e32 v197, 0xffff0000, v142
	s_waitcnt lgkmcnt(1)
	v_pk_fma_f32 v[114:115], v[134:135], v[132:133], v[114:115] op_sel_hi:[0,1,1] neg_lo:[1,0,0] neg_hi:[1,0,0]
	v_pk_fma_f32 v[110:111], v[134:135], v[124:125], v[110:111] op_sel_hi:[0,1,1] neg_lo:[1,0,0] neg_hi:[1,0,0]
	s_waitcnt lgkmcnt(0)
	v_pk_mul_f32 v[124:125], v[136:137], v[172:173] op_sel_hi:[0,1]
	v_pk_fma_f32 v[114:115], v[136:137], v[172:173], v[114:115] op_sel_hi:[0,1,1]
	v_div_fixup_f32 v134, v177, v176, 1.0
	v_pk_mul_f32 v[132:133], v[136:137], v[196:197] op_sel_hi:[0,1]
	v_pk_fma_f32 v[110:111], v[136:137], v[196:197], v[110:111] op_sel_hi:[0,1,1]
	v_pk_fma_f32 v[124:125], v[134:135], v[114:115], v[124:125] op_sel_hi:[0,1,1] neg_lo:[0,0,1] neg_hi:[0,0,1]
	v_pk_fma_f32 v[132:133], v[134:135], v[110:111], v[132:133] op_sel_hi:[0,1,1] neg_lo:[0,0,1] neg_hi:[0,0,1]
	v_cvt_pk_bf16_f32 v124, v124, v125
	v_cvt_pk_bf16_f32 v125, v132, v133
	ds_write_b64 v219, v[124:125]
	ds_read_b32 v124, v71 offset:44
	ds_read_b32 v132, v71 offset:76
	v_lshlrev_b32_e32 v146, 16, v147
	v_and_b32_e32 v147, 0xffff0000, v147
	v_lshlrev_b32_e32 v142, 16, v159
	s_waitcnt lgkmcnt(1)
	v_pk_fma_f32 v[110:111], v[124:125], v[126:127], v[110:111] op_sel_hi:[0,1,1] neg_lo:[1,0,0] neg_hi:[1,0,0]
	v_pk_fma_f32 v[114:115], v[124:125], v[198:199], v[114:115] op_sel_hi:[0,1,1] neg_lo:[1,0,0] neg_hi:[1,0,0]
	s_waitcnt lgkmcnt(0)
	v_pk_mul_f32 v[124:125], v[132:133], v[146:147] op_sel_hi:[0,1]
	v_pk_mul_f32 v[126:127], v[132:133], v[148:149] op_sel_hi:[0,1]
	v_pk_fma_f32 v[114:115], v[132:133], v[146:147], v[114:115] op_sel_hi:[0,1,1]
	v_pk_fma_f32 v[110:111], v[132:133], v[148:149], v[110:111] op_sel_hi:[0,1,1]
	v_div_fixup_f32 v132, v180, v178, 1.0
	v_pk_fma_f32 v[124:125], v[132:133], v[114:115], v[124:125] op_sel_hi:[0,1,1] neg_lo:[0,0,1] neg_hi:[0,0,1]
	v_pk_fma_f32 v[126:127], v[132:133], v[110:111], v[126:127] op_sel_hi:[0,1,1] neg_lo:[0,0,1] neg_hi:[0,0,1]
	v_cvt_pk_bf16_f32 v124, v124, v125
	v_cvt_pk_bf16_f32 v125, v126, v127
	ds_write_b64 v220, v[124:125]
	ds_read_b32 v124, v71 offset:48
	ds_read_b32 v126, v71 offset:80
	v_and_b32_e32 v143, 0xffff0000, v159
	v_lshlrev_b32_e32 v140, 16, v157
	v_and_b32_e32 v141, 0xffff0000, v157
	s_waitcnt lgkmcnt(1)
	v_pk_fma_f32 v[110:111], v[124:125], v[128:129], v[110:111] op_sel_hi:[0,1,1] neg_lo:[1,0,0] neg_hi:[1,0,0]
	v_pk_fma_f32 v[112:113], v[124:125], v[112:113], v[114:115] op_sel_hi:[0,1,1] neg_lo:[1,0,0] neg_hi:[1,0,0]
	v_lshlrev_b32_e32 v124, 16, v161
	v_and_b32_e32 v125, 0xffff0000, v161
	s_waitcnt lgkmcnt(0)
	v_pk_mul_f32 v[114:115], v[126:127], v[124:125] op_sel_hi:[0,1]
	v_pk_mul_f32 v[128:129], v[126:127], v[142:143] op_sel_hi:[0,1]
	v_pk_fma_f32 v[112:113], v[126:127], v[124:125], v[112:113] op_sel_hi:[0,1,1]
	v_pk_fma_f32 v[110:111], v[126:127], v[142:143], v[110:111] op_sel_hi:[0,1,1]
	v_div_fixup_f32 v126, v182, v181, 1.0
	v_pk_fma_f32 v[114:115], v[126:127], v[112:113], v[114:115] op_sel_hi:[0,1,1] neg_lo:[0,0,1] neg_hi:[0,0,1]
	v_pk_fma_f32 v[128:129], v[126:127], v[110:111], v[128:129] op_sel_hi:[0,1,1] neg_lo:[0,0,1] neg_hi:[0,0,1]
	v_cvt_pk_bf16_f32 v114, v114, v115
	v_cvt_pk_bf16_f32 v115, v128, v129
	ds_write_b64 v221, v[114:115]
	ds_read_b32 v114, v71 offset:52
	ds_read_b32 v128, v71 offset:84
	v_lshlrev_b32_e32 v126, 16, v158
	v_and_b32_e32 v127, 0xffff0000, v158
	v_lshlrev_b32_e32 v138, 16, v151
	s_waitcnt lgkmcnt(1)
	v_pk_fma_f32 v[110:111], v[114:115], v[130:131], v[110:111] op_sel_hi:[0,1,1] neg_lo:[1,0,0] neg_hi:[1,0,0]
	v_pk_fma_f32 v[112:113], v[114:115], v[200:201], v[112:113] op_sel_hi:[0,1,1] neg_lo:[1,0,0] neg_hi:[1,0,0]
	s_waitcnt lgkmcnt(0)
	v_pk_mul_f32 v[114:115], v[128:129], v[126:127] op_sel_hi:[0,1]
	v_pk_mul_f32 v[130:131], v[128:129], v[140:141] op_sel_hi:[0,1]
	v_pk_fma_f32 v[112:113], v[128:129], v[126:127], v[112:113] op_sel_hi:[0,1,1]
	v_pk_fma_f32 v[110:111], v[128:129], v[140:141], v[110:111] op_sel_hi:[0,1,1]
	v_div_fixup_f32 v128, v185, v183, 1.0
	v_pk_fma_f32 v[114:115], v[128:129], v[112:113], v[114:115] op_sel_hi:[0,1,1] neg_lo:[0,0,1] neg_hi:[0,0,1]
	v_pk_fma_f32 v[130:131], v[128:129], v[110:111], v[130:131] op_sel_hi:[0,1,1] neg_lo:[0,0,1] neg_hi:[0,0,1]
	v_cvt_pk_bf16_f32 v114, v114, v115
	v_cvt_pk_bf16_f32 v115, v130, v131
	ds_write_b64 v222, v[114:115]
	ds_read_b32 v114, v71 offset:56
	ds_read_b32 v128, v71 offset:88
	v_lshlrev_b32_e32 v130, 16, v156
	v_and_b32_e32 v131, 0xffff0000, v156
	v_and_b32_e32 v139, 0xffff0000, v151
	s_waitcnt lgkmcnt(1)
	v_pk_fma_f32 v[110:111], v[114:115], v[202:203], v[110:111] op_sel_hi:[0,1,1] neg_lo:[1,0,0] neg_hi:[1,0,0]
	v_pk_fma_f32 v[112:113], v[114:115], v[188:189], v[112:113] op_sel_hi:[0,1,1] neg_lo:[1,0,0] neg_hi:[1,0,0]
	s_waitcnt lgkmcnt(0)
	v_pk_mul_f32 v[114:115], v[128:129], v[130:131] op_sel_hi:[0,1]
	v_pk_mul_f32 v[132:133], v[128:129], v[138:139] op_sel_hi:[0,1]
	v_pk_fma_f32 v[112:113], v[128:129], v[130:131], v[112:113] op_sel_hi:[0,1,1]
	v_pk_fma_f32 v[110:111], v[128:129], v[138:139], v[110:111] op_sel_hi:[0,1,1]
	v_div_fixup_f32 v128, v187, v186, 1.0
	v_pk_fma_f32 v[114:115], v[128:129], v[112:113], v[114:115] op_sel_hi:[0,1,1] neg_lo:[0,0,1] neg_hi:[0,0,1]
	v_pk_fma_f32 v[132:133], v[128:129], v[110:111], v[132:133] op_sel_hi:[0,1,1] neg_lo:[0,0,1] neg_hi:[0,0,1]
	v_cvt_pk_bf16_f32 v114, v114, v115
	v_cvt_pk_bf16_f32 v115, v132, v133
	ds_write_b64 v223, v[114:115]
	ds_read_b32 v114, v71 offset:60
	ds_read_b32 v128, v71 offset:92
	v_lshlrev_b32_e32 v134, 16, v209
	v_and_b32_e32 v135, 0xffff0000, v209
	v_lshlrev_b32_e32 v136, 16, v208
	s_waitcnt lgkmcnt(1)
	v_pk_fma_f32 v[110:111], v[114:115], v[204:205], v[110:111] op_sel_hi:[0,1,1] neg_lo:[1,0,0] neg_hi:[1,0,0]
	v_pk_fma_f32 v[112:113], v[114:115], v[192:193], v[112:113] op_sel_hi:[0,1,1] neg_lo:[1,0,0] neg_hi:[1,0,0]
	v_and_b32_e32 v137, 0xffff0000, v208
	s_waitcnt lgkmcnt(0)
	v_pk_mul_f32 v[114:115], v[128:129], v[134:135] op_sel_hi:[0,1]
	v_pk_mul_f32 v[132:133], v[128:129], v[136:137] op_sel_hi:[0,1]
	v_pk_fma_f32 v[112:113], v[128:129], v[134:135], v[112:113] op_sel_hi:[0,1,1]
	v_pk_fma_f32 v[110:111], v[128:129], v[136:137], v[110:111] op_sel_hi:[0,1,1]
	v_div_fixup_f32 v128, v211, v210, 1.0
	v_pk_fma_f32 v[114:115], v[128:129], v[112:113], v[114:115] op_sel_hi:[0,1,1] neg_lo:[0,0,1] neg_hi:[0,0,1]
	v_pk_fma_f32 v[132:133], v[128:129], v[110:111], v[132:133] op_sel_hi:[0,1,1] neg_lo:[0,0,1] neg_hi:[0,0,1]
	v_cvt_pk_bf16_f32 v114, v114, v115
	v_cvt_pk_bf16_f32 v115, v132, v133
	ds_write_b64 v224, v[114:115]
	ds_read_b32 v114, v71 offset:64
	ds_read_b32 v156, v71 offset:96
	v_lshlrev_b32_e32 v128, 16, v213
	v_and_b32_e32 v129, 0xffff0000, v213
	v_lshlrev_b32_e32 v132, 16, v212
	s_waitcnt lgkmcnt(1)
	v_pk_fma_f32 v[110:111], v[114:115], v[168:169], v[110:111] op_sel_hi:[0,1,1] neg_lo:[1,0,0] neg_hi:[1,0,0]
	v_pk_fma_f32 v[112:113], v[114:115], v[118:119], v[112:113] op_sel_hi:[0,1,1] neg_lo:[1,0,0] neg_hi:[1,0,0]
	v_and_b32_e32 v133, 0xffff0000, v212
	v_readlane_b32 s2, v252, 4
	s_waitcnt lgkmcnt(0)
	v_pk_mul_f32 v[114:115], v[156:157], v[128:129] op_sel_hi:[0,1]
	v_pk_mul_f32 v[118:119], v[156:157], v[132:133] op_sel_hi:[0,1]
	v_pk_fma_f32 v[112:113], v[156:157], v[128:129], v[112:113] op_sel_hi:[0,1,1]
	v_pk_fma_f32 v[110:111], v[156:157], v[132:133], v[110:111] op_sel_hi:[0,1,1]
	v_div_fixup_f32 v156, v215, v214, 1.0
	s_lshl_b32 s2, s2, 9
	v_pk_fma_f32 v[118:119], v[156:157], v[110:111], v[118:119] op_sel_hi:[0,1,1] neg_lo:[0,0,1] neg_hi:[0,0,1]
	v_pk_fma_f32 v[114:115], v[156:157], v[112:113], v[114:115] op_sel_hi:[0,1,1] neg_lo:[0,0,1] neg_hi:[0,0,1]
	s_add_i32 s2, s2, 0
	v_bitop3_b32 v151, v184, s3, v240 bitop3:0x6c
	v_cvt_pk_bf16_f32 v114, v114, v115
	v_cvt_pk_bf16_f32 v115, v118, v119
	v_add3_u32 v118, s2, v151, v150
	s_min_i32 s2, s92, -3
	s_add_i32 s2, s2, 11
	v_cvt_f32_i32_e32 v161, s2
	ds_write_b64 v118, v[114:115]
	ds_read_b32 v114, v71 offset:68
	ds_read_b32 v118, v71 offset:100
	v_div_scale_f32 v165, s[2:3], v161, v161, 1.0
	v_rcp_f32_e32 v166, v165
	v_cndmask_b32_e64 v115, v145, 0, s[50:51]
	v_cndmask_b32_e64 v119, v144, 0, s[50:51]
	s_waitcnt lgkmcnt(1)
	v_pk_fma_f32 v[144:145], v[114:115], v[194:195], v[110:111] op_sel_hi:[0,1,1] neg_lo:[1,0,0] neg_hi:[1,0,0]
	v_pk_fma_f32 v[112:113], v[114:115], v[190:191], v[112:113] op_sel_hi:[0,1,1] neg_lo:[1,0,0] neg_hi:[1,0,0]
	v_lshlrev_b32_e32 v110, 16, v119
	v_and_b32_e32 v111, 0xffff0000, v119
	v_lshlrev_b32_e32 v114, 16, v115
	v_and_b32_e32 v115, 0xffff0000, v115
	s_waitcnt lgkmcnt(0)
	v_pk_mul_f32 v[156:157], v[118:119], v[110:111] op_sel_hi:[0,1]
	v_pk_mul_f32 v[158:159], v[118:119], v[114:115] op_sel_hi:[0,1]
	v_pk_fma_f32 v[112:113], v[118:119], v[110:111], v[112:113] op_sel_hi:[0,1,1]
	v_pk_fma_f32 v[118:119], v[118:119], v[114:115], v[144:145] op_sel_hi:[0,1,1]
	v_fma_f32 v144, -v165, v166, 1.0
	v_fmac_f32_e32 v166, v144, v166
	v_div_scale_f32 v144, vcc, 1.0, v161, 1.0
	v_mul_f32_e32 v145, v144, v166
	v_fma_f32 v168, -v165, v145, v144
	v_fmac_f32_e32 v145, v168, v166
	v_fma_f32 v144, -v165, v145, v144
	v_div_fmas_f32 v144, v144, v166, v145
	v_div_fixup_f32 v144, v144, v161, 1.0
	v_readlane_b32 s2, v252, 3
	v_pk_fma_f32 v[158:159], v[144:145], v[118:119], v[158:159] op_sel_hi:[0,1,1] neg_lo:[0,0,1] neg_hi:[0,0,1]
	v_pk_fma_f32 v[144:145], v[144:145], v[112:113], v[156:157] op_sel_hi:[0,1,1] neg_lo:[0,0,1] neg_hi:[0,0,1]
	s_lshl_b32 s2, s2, 9
	s_movk_i32 s3, 0xa0
	v_cvt_pk_bf16_f32 v156, v144, v145
	s_add_i32 s2, s2, 0
	v_bitop3_b32 v144, v184, s3, v240 bitop3:0x6c
	v_add3_u32 v145, s2, v144, v150
	v_cvt_pk_bf16_f32 v157, v158, v159
	ds_write_b64 v145, v[156:157]
	ds_read_b32 v156, v71 offset:72
	s_min_i32 s2, s92, -4
	s_waitcnt vmcnt(3)
	v_cndmask_b32_e64 v145, v122, 0, s[48:49]
	s_add_i32 s2, s2, 12
	ds_read_b32 v122, v71 offset:104
	s_waitcnt lgkmcnt(1)
	v_pk_fma_f32 v[158:159], v[156:157], v[196:197], v[118:119] op_sel_hi:[0,1,1] neg_lo:[1,0,0] neg_hi:[1,0,0]
	v_pk_fma_f32 v[156:157], v[156:157], v[172:173], v[112:113] op_sel_hi:[0,1,1] neg_lo:[1,0,0] neg_hi:[1,0,0]
	v_lshlrev_b32_e32 v112, 16, v145
	v_and_b32_e32 v113, 0xffff0000, v145
	v_cvt_f32_i32_e32 v145, s2
	v_cndmask_b32_e64 v123, v123, 0, s[48:49]
	global_load_dwordx2 v[106:107], v[106:107], off
	v_lshlrev_b32_e32 v118, 16, v123
	v_div_scale_f32 v161, s[2:3], v145, v145, 1.0
	v_rcp_f32_e32 v165, v161
	v_and_b32_e32 v119, 0xffff0000, v123
	s_waitcnt lgkmcnt(0)
	v_pk_mul_f32 v[168:169], v[122:123], v[112:113] op_sel_hi:[0,1]
	v_pk_mul_f32 v[172:173], v[122:123], v[118:119] op_sel_hi:[0,1]
	v_pk_fma_f32 v[156:157], v[122:123], v[112:113], v[156:157] op_sel_hi:[0,1,1]
	v_pk_fma_f32 v[122:123], v[122:123], v[118:119], v[158:159] op_sel_hi:[0,1,1]
	v_fma_f32 v158, -v161, v165, 1.0
	v_fmac_f32_e32 v165, v158, v165
	v_div_scale_f32 v158, vcc, 1.0, v145, 1.0
	v_mul_f32_e32 v159, v158, v165
	v_fma_f32 v166, -v161, v159, v158
	v_fmac_f32_e32 v159, v166, v165
	v_fma_f32 v158, -v161, v159, v158
	v_readlane_b32 s2, v254, 63
	v_div_fmas_f32 v158, v158, v165, v159
	s_lshl_b32 s2, s2, 9
	s_movk_i32 s3, 0xb0
	v_div_fixup_f32 v158, v158, v145, 1.0
	s_add_i32 s2, s2, 0
	v_bitop3_b32 v145, v184, s3, v240 bitop3:0x6c
	v_add3_u32 v161, s2, v145, v150
	s_min_i32 s2, s92, -5
	v_pk_fma_f32 v[172:173], v[158:159], v[122:123], v[172:173] op_sel_hi:[0,1,1] neg_lo:[0,0,1] neg_hi:[0,0,1]
	v_pk_fma_f32 v[158:159], v[158:159], v[156:157], v[168:169] op_sel_hi:[0,1,1] neg_lo:[0,0,1] neg_hi:[0,0,1]
	s_add_i32 s2, s2, 13
	v_cvt_pk_bf16_f32 v158, v158, v159
	v_cvt_pk_bf16_f32 v159, v172, v173
	ds_write_b64 v161, v[158:159]
	v_cvt_f32_i32_e32 v161, s2
	ds_read_b32 v158, v71 offset:76
	ds_read_b32 v166, v71 offset:108
	s_waitcnt vmcnt(3)
	v_cndmask_b32_e64 v159, v117, 0, s[46:47]
	v_div_scale_f32 v165, s[2:3], v161, v161, 1.0
	v_rcp_f32_e32 v171, v165
	v_cndmask_b32_e64 v117, v116, 0, s[46:47]
	s_waitcnt lgkmcnt(1)
	v_pk_fma_f32 v[146:147], v[158:159], v[146:147], v[156:157] op_sel_hi:[0,1,1] neg_lo:[1,0,0] neg_hi:[1,0,0]
	v_lshlrev_b32_e32 v116, 16, v117
	v_and_b32_e32 v117, 0xffff0000, v117
	s_waitcnt lgkmcnt(0)
	v_pk_fma_f32 v[168:169], v[166:167], v[116:117], v[146:147] op_sel_hi:[0,1,1]
	v_fma_f32 v146, -v165, v171, 1.0
	v_fmac_f32_e32 v171, v146, v171
	v_div_scale_f32 v146, vcc, 1.0, v161, 1.0
	v_pk_fma_f32 v[148:149], v[158:159], v[148:149], v[122:123] op_sel_hi:[0,1,1] neg_lo:[1,0,0] neg_hi:[1,0,0]
	v_lshlrev_b32_e32 v122, 16, v159
	v_and_b32_e32 v123, 0xffff0000, v159
	v_mul_f32_e32 v147, v146, v171
	v_pk_mul_f32 v[156:157], v[166:167], v[116:117] op_sel_hi:[0,1]
	v_pk_mul_f32 v[158:159], v[166:167], v[122:123] op_sel_hi:[0,1]
	v_pk_fma_f32 v[148:149], v[166:167], v[122:123], v[148:149] op_sel_hi:[0,1,1]
	v_fma_f32 v166, -v165, v147, v146
	v_fmac_f32_e32 v147, v166, v171
	v_fma_f32 v146, -v165, v147, v146
	v_div_fmas_f32 v146, v146, v171, v147
	v_div_fixup_f32 v146, v146, v161, 1.0
	v_readlane_b32 s2, v254, 61
	v_pk_fma_f32 v[158:159], v[146:147], v[148:149], v[158:159] op_sel_hi:[0,1,1] neg_lo:[0,0,1] neg_hi:[0,0,1]
	v_pk_fma_f32 v[146:147], v[146:147], v[168:169], v[156:157] op_sel_hi:[0,1,1] neg_lo:[0,0,1] neg_hi:[0,0,1]
	s_lshl_b32 s2, s2, 9
	s_movk_i32 s3, 0xc0
	v_cvt_pk_bf16_f32 v156, v146, v147
	s_add_i32 s2, s2, 0
	v_bitop3_b32 v146, v184, s3, v240 bitop3:0x6c
	v_add3_u32 v147, s2, v146, v150
	v_cvt_pk_bf16_f32 v157, v158, v159
	ds_write_b64 v147, v[156:157]
	s_min_i32 s2, s92, -6
	ds_read_b32 v156, v71 offset:80
	ds_read_b32 v158, v71 offset:112
	s_add_i32 s2, s2, 14
	v_cvt_f32_i32_e32 v161, s2
	s_waitcnt vmcnt(2)
	v_cndmask_b32_e64 v147, v121, 0, s[44:45]
	s_waitcnt lgkmcnt(1)
	v_pk_fma_f32 v[142:143], v[156:157], v[142:143], v[148:149] op_sel_hi:[0,1,1] neg_lo:[1,0,0] neg_hi:[1,0,0]
	v_pk_fma_f32 v[148:149], v[156:157], v[124:125], v[168:169] op_sel_hi:[0,1,1] neg_lo:[1,0,0] neg_hi:[1,0,0]
	v_lshlrev_b32_e32 v124, 16, v147
	v_and_b32_e32 v125, 0xffff0000, v147
	v_div_scale_f32 v147, s[2:3], v161, v161, 1.0
	v_rcp_f32_e32 v165, v147
	v_cndmask_b32_e64 v121, v120, 0, s[44:45]
	v_lshlrev_b32_e32 v120, 16, v121
	v_and_b32_e32 v121, 0xffff0000, v121
	s_waitcnt lgkmcnt(0)
	v_pk_mul_f32 v[156:157], v[158:159], v[120:121] op_sel_hi:[0,1]
	v_pk_mul_f32 v[168:169], v[158:159], v[124:125] op_sel_hi:[0,1]
	v_pk_fma_f32 v[148:149], v[158:159], v[120:121], v[148:149] op_sel_hi:[0,1,1]
	v_pk_fma_f32 v[158:159], v[158:159], v[124:125], v[142:143] op_sel_hi:[0,1,1]
	v_fma_f32 v142, -v147, v165, 1.0
	v_fmac_f32_e32 v165, v142, v165
	v_div_scale_f32 v142, vcc, 1.0, v161, 1.0
	v_mul_f32_e32 v143, v142, v165
	v_fma_f32 v166, -v147, v143, v142
	v_fmac_f32_e32 v143, v166, v165
	v_fma_f32 v142, -v147, v143, v142
	v_div_fmas_f32 v142, v142, v165, v143
	v_div_fixup_f32 v142, v142, v161, 1.0
	v_readlane_b32 s2, v254, 59
	v_pk_fma_f32 v[168:169], v[142:143], v[158:159], v[168:169] op_sel_hi:[0,1,1] neg_lo:[0,0,1] neg_hi:[0,0,1]
	v_pk_fma_f32 v[142:143], v[142:143], v[148:149], v[156:157] op_sel_hi:[0,1,1] neg_lo:[0,0,1] neg_hi:[0,0,1]
	s_lshl_b32 s2, s2, 9
	v_cvt_pk_bf16_f32 v156, v142, v143
	s_add_i32 s2, s2, 0
	v_bitop3_b32 v142, v184, s70, v240 bitop3:0x6c
	v_add3_u32 v143, s2, v142, v150
	v_cvt_pk_bf16_f32 v157, v168, v169
	ds_write_b64 v143, v[156:157]
	s_min_i32 s2, s92, -7
	ds_read_b32 v156, v71 offset:84
	ds_read_b32 v166, v71 offset:116
	s_add_i32 s2, s2, 15
	v_cvt_f32_i32_e32 v147, s2
	s_waitcnt vmcnt(1)
	v_cndmask_b32_e64 v143, v109, 0, s[42:43]
	s_waitcnt lgkmcnt(1)
	v_pk_fma_f32 v[148:149], v[156:157], v[126:127], v[148:149] op_sel_hi:[0,1,1] neg_lo:[1,0,0] neg_hi:[1,0,0]
	v_lshlrev_b32_e32 v126, 16, v143
	v_and_b32_e32 v127, 0xffff0000, v143
	v_div_scale_f32 v143, s[2:3], v147, v147, 1.0
	v_rcp_f32_e32 v161, v143
	v_pk_fma_f32 v[140:141], v[156:157], v[140:141], v[158:159] op_sel_hi:[0,1,1] neg_lo:[1,0,0] neg_hi:[1,0,0]
	s_waitcnt lgkmcnt(0)
	v_pk_fma_f32 v[168:169], v[166:167], v[126:127], v[140:141] op_sel_hi:[0,1,1]
	v_cndmask_b32_e64 v109, v108, 0, s[42:43]
	v_fma_f32 v140, -v143, v161, 1.0
	v_fmac_f32_e32 v161, v140, v161
	v_div_scale_f32 v140, vcc, 1.0, v147, 1.0
	v_mul_f32_e32 v141, v140, v161
	v_fma_f32 v165, -v143, v141, v140
	v_fmac_f32_e32 v141, v165, v161
	v_fma_f32 v140, -v143, v141, v140
	v_lshlrev_b32_e32 v108, 16, v109
	v_and_b32_e32 v109, 0xffff0000, v109
	v_div_fmas_f32 v140, v140, v161, v141
	v_pk_mul_f32 v[156:157], v[166:167], v[108:109] op_sel_hi:[0,1]
	v_pk_mul_f32 v[158:159], v[166:167], v[126:127] op_sel_hi:[0,1]
	v_pk_fma_f32 v[148:149], v[166:167], v[108:109], v[148:149] op_sel_hi:[0,1,1]
	v_div_fixup_f32 v140, v140, v147, 1.0
	v_readlane_b32 s2, v254, 57
	v_pk_fma_f32 v[158:159], v[140:141], v[168:169], v[158:159] op_sel_hi:[0,1,1] neg_lo:[0,0,1] neg_hi:[0,0,1]
	v_pk_fma_f32 v[140:141], v[140:141], v[148:149], v[156:157] op_sel_hi:[0,1,1] neg_lo:[0,0,1] neg_hi:[0,0,1]
	s_lshl_b32 s2, s2, 9
	v_cvt_pk_bf16_f32 v156, v140, v141
	s_add_i32 s2, s2, 0
	v_bitop3_b32 v140, v184, s71, v240 bitop3:0x6c
	v_add3_u32 v141, s2, v140, v150
	v_cvt_pk_bf16_f32 v157, v158, v159
	ds_write_b64 v141, v[156:157]
	s_min_i32 s2, s92, -8
	ds_read_b32 v156, v71 offset:88
	ds_read_b32 v158, v71 offset:120
	s_add_i32 s2, s2, 16
	v_cvt_f32_i32_e32 v143, s2
	s_waitcnt vmcnt(0)
	v_cndmask_b32_e64 v141, v107, 0, s[40:41]
	s_waitcnt lgkmcnt(1)
	v_pk_fma_f32 v[148:149], v[156:157], v[130:131], v[148:149] op_sel_hi:[0,1,1] neg_lo:[1,0,0] neg_hi:[1,0,0]
	v_lshlrev_b32_e32 v130, 16, v141
	v_and_b32_e32 v131, 0xffff0000, v141
	v_div_scale_f32 v141, s[2:3], v143, v143, 1.0
	v_rcp_f32_e32 v147, v141
	v_cndmask_b32_e64 v107, v106, 0, s[40:41]
	v_pk_fma_f32 v[138:139], v[156:157], v[138:139], v[168:169] op_sel_hi:[0,1,1] neg_lo:[1,0,0] neg_hi:[1,0,0]
	v_lshlrev_b32_e32 v106, 16, v107
	v_and_b32_e32 v107, 0xffff0000, v107
	s_waitcnt lgkmcnt(0)
	v_pk_mul_f32 v[156:157], v[158:159], v[106:107] op_sel_hi:[0,1]
	v_pk_mul_f32 v[168:169], v[158:159], v[130:131] op_sel_hi:[0,1]
	v_pk_fma_f32 v[148:149], v[158:159], v[106:107], v[148:149] op_sel_hi:[0,1,1]
	v_pk_fma_f32 v[158:159], v[158:159], v[130:131], v[138:139] op_sel_hi:[0,1,1]
	v_fma_f32 v138, -v141, v147, 1.0
	v_fmac_f32_e32 v147, v138, v147
	v_div_scale_f32 v138, vcc, 1.0, v143, 1.0
	v_mul_f32_e32 v139, v138, v147
	v_fma_f32 v161, -v141, v139, v138
	v_fmac_f32_e32 v139, v161, v147
	v_fma_f32 v138, -v141, v139, v138
	v_div_fmas_f32 v138, v138, v147, v139
	v_div_fixup_f32 v138, v138, v143, 1.0
	v_pk_fma_f32 v[168:169], v[138:139], v[158:159], v[168:169] op_sel_hi:[0,1,1] neg_lo:[0,0,1] neg_hi:[0,0,1]
	v_pk_fma_f32 v[138:139], v[138:139], v[148:149], v[156:157] op_sel_hi:[0,1,1] neg_lo:[0,0,1] neg_hi:[0,0,1]
	s_lshl_b32 s2, s95, 9
	v_cvt_pk_bf16_f32 v156, v138, v139
	s_add_i32 s2, s2, 0
	v_bitop3_b32 v138, v184, s76, v240 bitop3:0x6c
	v_add3_u32 v139, s2, v138, v150
	v_cvt_pk_bf16_f32 v157, v168, v169
	ds_write_b64 v139, v[156:157]
	s_min_i32 s2, s92, -9
	ds_read_b32 v156, v71 offset:92
	ds_read_b32 v166, v71 offset:124
	s_add_i32 s2, s2, 17
	v_cvt_f32_i32_e32 v141, s2
	v_cndmask_b32_e64 v139, v105, 0, s[38:39]
	s_waitcnt lgkmcnt(1)
	v_pk_fma_f32 v[148:149], v[156:157], v[134:135], v[148:149] op_sel_hi:[0,1,1] neg_lo:[1,0,0] neg_hi:[1,0,0]
	v_lshlrev_b32_e32 v134, 16, v139
	v_and_b32_e32 v135, 0xffff0000, v139
	v_div_scale_f32 v139, s[2:3], v141, v141, 1.0
	v_rcp_f32_e32 v143, v139
	v_cndmask_b32_e64 v105, v104, 0, s[38:39]
	v_readlane_b32 s2, v254, 55
	v_pk_fma_f32 v[136:137], v[156:157], v[136:137], v[158:159] op_sel_hi:[0,1,1] neg_lo:[1,0,0] neg_hi:[1,0,0]
	v_fma_f32 v147, -v139, v143, 1.0
	v_fmac_f32_e32 v143, v147, v143
	v_div_scale_f32 v147, vcc, 1.0, v141, 1.0
	v_mul_f32_e32 v161, v147, v143
	v_fma_f32 v165, -v139, v161, v147
	v_fmac_f32_e32 v161, v165, v143
	v_fma_f32 v139, -v139, v161, v147
	v_lshlrev_b32_e32 v104, 16, v105
	v_and_b32_e32 v105, 0xffff0000, v105
	v_div_fmas_f32 v139, v139, v143, v161
	s_lshl_b32 s2, s2, 9
	s_waitcnt lgkmcnt(0)
	v_pk_mul_f32 v[156:157], v[166:167], v[104:105] op_sel_hi:[0,1]
	v_pk_mul_f32 v[158:159], v[166:167], v[134:135] op_sel_hi:[0,1]
	v_pk_fma_f32 v[148:149], v[166:167], v[104:105], v[148:149] op_sel_hi:[0,1,1]
	v_pk_fma_f32 v[136:137], v[166:167], v[134:135], v[136:137] op_sel_hi:[0,1,1]
	v_div_fixup_f32 v166, v139, v141, 1.0
	s_add_i32 s2, s2, 0
	v_pk_fma_f32 v[156:157], v[166:167], v[148:149], v[156:157] op_sel_hi:[0,1,1] neg_lo:[0,0,1] neg_hi:[0,0,1]
	v_add3_u32 v139, s2, v179, v150
	v_pk_fma_f32 v[158:159], v[166:167], v[136:137], v[158:159] op_sel_hi:[0,1,1] neg_lo:[0,0,1] neg_hi:[0,0,1]
	v_cvt_pk_bf16_f32 v156, v156, v157
	v_cvt_pk_bf16_f32 v157, v158, v159
	ds_write_b64 v139, v[156:157]
	s_min_i32 s2, s92, -10
	ds_read_b32 v156, v71 offset:96
	ds_read_b32 v158, v71 offset:128
	s_add_i32 s2, s2, 18
	v_cvt_f32_i32_e32 v141, s2
	v_cndmask_b32_e64 v139, v103, 0, s[36:37]
	s_waitcnt lgkmcnt(1)
	v_pk_fma_f32 v[136:137], v[156:157], v[132:133], v[136:137] op_sel_hi:[0,1,1] neg_lo:[1,0,0] neg_hi:[1,0,0]
	v_lshlrev_b32_e32 v132, 16, v139
	v_and_b32_e32 v133, 0xffff0000, v139
	v_div_scale_f32 v139, s[2:3], v141, v141, 1.0
	v_rcp_f32_e32 v143, v139
	v_cndmask_b32_e64 v103, v102, 0, s[36:37]
	v_pk_fma_f32 v[128:129], v[156:157], v[128:129], v[148:149] op_sel_hi:[0,1,1] neg_lo:[1,0,0] neg_hi:[1,0,0]
	v_lshlrev_b32_e32 v102, 16, v103
	v_fma_f32 v147, -v139, v143, 1.0
	v_and_b32_e32 v103, 0xffff0000, v103
	v_fmac_f32_e32 v143, v147, v143
	v_div_scale_f32 v147, vcc, 1.0, v141, 1.0
	s_waitcnt lgkmcnt(0)
	v_pk_mul_f32 v[148:149], v[158:159], v[102:103] op_sel_hi:[0,1]
	v_pk_mul_f32 v[156:157], v[158:159], v[132:133] op_sel_hi:[0,1]
	v_pk_fma_f32 v[128:129], v[158:159], v[102:103], v[128:129] op_sel_hi:[0,1,1]
	v_pk_fma_f32 v[136:137], v[158:159], v[132:133], v[136:137] op_sel_hi:[0,1,1]
	v_mul_f32_e32 v158, v147, v143
	v_fma_f32 v159, -v139, v158, v147
	v_fmac_f32_e32 v158, v159, v143
	v_fma_f32 v139, -v139, v158, v147
	v_readlane_b32 s2, v254, 53
	v_div_fmas_f32 v139, v139, v143, v158
	s_lshl_b32 s2, s2, 9
	v_div_fixup_f32 v158, v139, v141, 1.0
	s_add_i32 s2, s2, 0
	v_pk_fma_f32 v[148:149], v[158:159], v[128:129], v[148:149] op_sel_hi:[0,1,1] neg_lo:[0,0,1] neg_hi:[0,0,1]
	v_add3_u32 v139, s2, v175, v150
	v_pk_fma_f32 v[156:157], v[158:159], v[136:137], v[156:157] op_sel_hi:[0,1,1] neg_lo:[0,0,1] neg_hi:[0,0,1]
	v_cvt_pk_bf16_f32 v148, v148, v149
	v_cvt_pk_bf16_f32 v149, v156, v157
	ds_write_b64 v139, v[148:149]
	s_min_i32 s2, s92, -11
	ds_read_b32 v148, v71 offset:100
	ds_read_b32 v156, v71 offset:132
	s_add_i32 s2, s2, 19
	v_cvt_f32_i32_e32 v141, s2
	v_cndmask_b32_e64 v139, v101, 0, s[34:35]
	s_waitcnt lgkmcnt(1)
	v_pk_fma_f32 v[110:111], v[148:149], v[110:111], v[128:129] op_sel_hi:[0,1,1] neg_lo:[1,0,0] neg_hi:[1,0,0]
	v_lshlrev_b32_e32 v128, 16, v139
	v_and_b32_e32 v129, 0xffff0000, v139
	v_div_scale_f32 v139, s[2:3], v141, v141, 1.0
	v_rcp_f32_e32 v143, v139
	v_cndmask_b32_e64 v101, v100, 0, s[34:35]
	v_pk_fma_f32 v[114:115], v[148:149], v[114:115], v[136:137] op_sel_hi:[0,1,1] neg_lo:[1,0,0] neg_hi:[1,0,0]
	v_lshlrev_b32_e32 v100, 16, v101
	v_fma_f32 v147, -v139, v143, 1.0
	v_and_b32_e32 v101, 0xffff0000, v101
	v_fmac_f32_e32 v143, v147, v143
	v_div_scale_f32 v147, vcc, 1.0, v141, 1.0
	s_waitcnt lgkmcnt(0)
	v_pk_mul_f32 v[136:137], v[156:157], v[100:101] op_sel_hi:[0,1]
	v_pk_mul_f32 v[148:149], v[156:157], v[128:129] op_sel_hi:[0,1]
	v_pk_fma_f32 v[110:111], v[156:157], v[100:101], v[110:111] op_sel_hi:[0,1,1]
	v_pk_fma_f32 v[114:115], v[156:157], v[128:129], v[114:115] op_sel_hi:[0,1,1]
	v_mul_f32_e32 v156, v147, v143
	v_fma_f32 v157, -v139, v156, v147
	v_fmac_f32_e32 v156, v157, v143
	v_readlane_b32 s2, v254, 51
	v_fma_f32 v139, -v139, v156, v147
	s_lshl_b32 s2, s2, 9
	v_div_fmas_f32 v139, v139, v143, v156
	s_add_i32 s2, s2, 0
	v_div_fixup_f32 v156, v139, v141, 1.0
	v_add3_u32 v139, s2, v170, v150
	s_min_i32 s2, s92, -12
	v_pk_fma_f32 v[136:137], v[156:157], v[110:111], v[136:137] op_sel_hi:[0,1,1] neg_lo:[0,0,1] neg_hi:[0,0,1]
	s_add_i32 s2, s2, 20
	v_pk_fma_f32 v[148:149], v[156:157], v[114:115], v[148:149] op_sel_hi:[0,1,1] neg_lo:[0,0,1] neg_hi:[0,0,1]
	v_cvt_pk_bf16_f32 v136, v136, v137
	v_cvt_pk_bf16_f32 v137, v148, v149
	ds_write_b64 v139, v[136:137]
	v_cvt_f32_i32_e32 v139, s2
	ds_read_b32 v136, v71 offset:104
	ds_read_b32 v148, v71 offset:136
	v_cndmask_b32_e64 v137, v99, 0, s[30:31]
	v_div_scale_f32 v141, s[2:3], v139, v139, 1.0
	v_rcp_f32_e32 v143, v141
	v_cndmask_b32_e64 v99, v98, 0, s[30:31]
	s_waitcnt lgkmcnt(1)
	v_pk_fma_f32 v[118:119], v[136:137], v[118:119], v[114:115] op_sel_hi:[0,1,1] neg_lo:[1,0,0] neg_hi:[1,0,0]
	v_pk_fma_f32 v[110:111], v[136:137], v[112:113], v[110:111] op_sel_hi:[0,1,1] neg_lo:[1,0,0] neg_hi:[1,0,0]
	v_fma_f32 v147, -v141, v143, 1.0
	v_lshlrev_b32_e32 v98, 16, v99
	v_and_b32_e32 v99, 0xffff0000, v99
	v_lshlrev_b32_e32 v114, 16, v137
	v_and_b32_e32 v115, 0xffff0000, v137
	v_fmac_f32_e32 v143, v147, v143
	v_div_scale_f32 v147, vcc, 1.0, v139, 1.0
	s_waitcnt lgkmcnt(0)
	v_pk_mul_f32 v[112:113], v[148:149], v[98:99] op_sel_hi:[0,1]
	v_pk_mul_f32 v[136:137], v[148:149], v[114:115] op_sel_hi:[0,1]
	v_pk_fma_f32 v[110:111], v[148:149], v[98:99], v[110:111] op_sel_hi:[0,1,1]
	v_pk_fma_f32 v[118:119], v[148:149], v[114:115], v[118:119] op_sel_hi:[0,1,1]
	v_mul_f32_e32 v148, v147, v143
	v_fma_f32 v149, -v141, v148, v147
	v_fmac_f32_e32 v148, v149, v143
	v_fma_f32 v141, -v141, v148, v147
	v_div_fmas_f32 v141, v141, v143, v148
	v_readlane_b32 s2, v254, 47
	v_div_fixup_f32 v148, v141, v139, 1.0
	s_lshl_b32 s2, s2, 9
	v_pk_fma_f32 v[136:137], v[148:149], v[118:119], v[136:137] op_sel_hi:[0,1,1] neg_lo:[0,0,1] neg_hi:[0,0,1]
	v_pk_fma_f32 v[112:113], v[148:149], v[110:111], v[112:113] op_sel_hi:[0,1,1] neg_lo:[0,0,1] neg_hi:[0,0,1]
	s_add_i32 s2, s2, 0
	v_cvt_pk_bf16_f32 v112, v112, v113
	v_cvt_pk_bf16_f32 v113, v136, v137
	v_add3_u32 v136, s2, v167, v150
	s_min_i32 s2, s92, -13
	s_add_i32 s2, s2, 21
	v_cvt_f32_i32_e32 v137, s2
	ds_write_b64 v136, v[112:113]
	ds_read_b32 v112, v71 offset:108
	ds_read_b32 v136, v71 offset:140
	v_div_scale_f32 v139, s[2:3], v137, v137, 1.0
	v_rcp_f32_e32 v141, v139
	v_cndmask_b32_e64 v113, v97, 0, s[28:29]
	v_cndmask_b32_e64 v97, v96, 0, s[28:29]
	s_waitcnt lgkmcnt(1)
	v_pk_fma_f32 v[118:119], v[112:113], v[122:123], v[118:119] op_sel_hi:[0,1,1] neg_lo:[1,0,0] neg_hi:[1,0,0]
	v_pk_fma_f32 v[110:111], v[112:113], v[116:117], v[110:111] op_sel_hi:[0,1,1] neg_lo:[1,0,0] neg_hi:[1,0,0]
	v_lshlrev_b32_e32 v96, 16, v97
	v_and_b32_e32 v97, 0xffff0000, v97
	v_lshlrev_b32_e32 v112, 16, v113
	v_and_b32_e32 v113, 0xffff0000, v113
	s_waitcnt lgkmcnt(0)
	v_pk_mul_f32 v[116:117], v[136:137], v[96:97] op_sel_hi:[0,1]
	v_pk_mul_f32 v[122:123], v[136:137], v[112:113] op_sel_hi:[0,1]
	v_pk_fma_f32 v[110:111], v[136:137], v[96:97], v[110:111] op_sel_hi:[0,1,1]
	v_pk_fma_f32 v[118:119], v[136:137], v[112:113], v[118:119] op_sel_hi:[0,1,1]
	v_fma_f32 v136, -v139, v141, 1.0
	v_fmac_f32_e32 v141, v136, v141
	v_div_scale_f32 v136, vcc, 1.0, v137, 1.0
	v_mul_f32_e32 v143, v136, v141
	v_fma_f32 v147, -v139, v143, v136
	v_fmac_f32_e32 v143, v147, v141
	v_fma_f32 v136, -v139, v143, v136
	v_div_fmas_f32 v136, v136, v141, v143
	v_readlane_b32 s2, v252, 2
	v_div_fixup_f32 v136, v136, v137, 1.0
	s_lshl_b32 s2, s2, 9
	v_pk_fma_f32 v[122:123], v[136:137], v[118:119], v[122:123] op_sel_hi:[0,1,1] neg_lo:[0,0,1] neg_hi:[0,0,1]
	v_pk_fma_f32 v[116:117], v[136:137], v[110:111], v[116:117] op_sel_hi:[0,1,1] neg_lo:[0,0,1] neg_hi:[0,0,1]
	s_add_i32 s2, s2, 0
	v_cvt_pk_bf16_f32 v116, v116, v117
	v_cvt_pk_bf16_f32 v117, v122, v123
	v_add3_u32 v122, s2, v164, v150
	ds_write_b64 v122, v[116:117]
	ds_read_b32 v116, v71 offset:112
	ds_read_b32 v122, v71 offset:144
	s_min_i32 s2, s92, -14
	v_cndmask_b32_e64 v117, v79, v73, s[8:9]
	s_add_i32 s2, s2, 22
	s_waitcnt lgkmcnt(1)
	v_pk_fma_f32 v[118:119], v[116:117], v[124:125], v[118:119] op_sel_hi:[0,1,1] neg_lo:[1,0,0] neg_hi:[1,0,0]
	v_pk_fma_f32 v[120:121], v[116:117], v[120:121], v[110:111] op_sel_hi:[0,1,1] neg_lo:[1,0,0] neg_hi:[1,0,0]
	v_cvt_f32_i32_e32 v116, s2
	v_cndmask_b32_e64 v79, v95, 0, s[26:27]
	v_cndmask_b32_e64 v95, v94, 0, s[26:27]
	v_lshlrev_b32_e32 v94, 16, v95
	v_and_b32_e32 v95, 0xffff0000, v95
	v_lshlrev_b32_e32 v110, 16, v79
	v_and_b32_e32 v111, 0xffff0000, v79
	v_div_scale_f32 v79, s[2:3], v116, v116, 1.0
	s_waitcnt lgkmcnt(0)
	v_pk_mul_f32 v[124:125], v[122:123], v[94:95] op_sel_hi:[0,1]
	v_rcp_f32_e32 v123, v79
	v_readlane_b32 s2, v252, 1
	s_lshl_b32 s2, s2, 9
	s_add_i32 s2, s2, 0
	v_pk_mul_f32 v[136:137], v[122:123], v[110:111] op_sel_hi:[0,1]
	v_pk_fma_f32 v[120:121], v[122:123], v[94:95], v[120:121] op_sel_hi:[0,1,1]
	v_pk_fma_f32 v[118:119], v[122:123], v[110:111], v[118:119] op_sel_hi:[0,1,1]
	v_fma_f32 v122, -v79, v123, 1.0
	v_fmac_f32_e32 v123, v122, v123
	v_div_scale_f32 v122, vcc, 1.0, v116, 1.0
	v_mul_f32_e32 v139, v122, v123
	v_fma_f32 v141, -v79, v139, v122
	v_fmac_f32_e32 v139, v141, v123
	v_fma_f32 v79, -v79, v139, v122
	v_div_fmas_f32 v79, v79, v123, v139
	v_div_fixup_f32 v116, v79, v116, 1.0
	v_pk_fma_f32 v[124:125], v[116:117], v[120:121], v[124:125] op_sel_hi:[0,1,1] neg_lo:[0,0,1] neg_hi:[0,0,1]
	v_add3_u32 v79, s2, v163, v150
	s_min_i32 s2, s92, -15
	v_pk_fma_f32 v[122:123], v[116:117], v[118:119], v[136:137] op_sel_hi:[0,1,1] neg_lo:[0,0,1] neg_hi:[0,0,1]
	v_cvt_pk_bf16_f32 v124, v124, v125
	v_cvt_pk_bf16_f32 v125, v122, v123
	s_add_i32 s2, s2, 23
	ds_write_b64 v79, v[124:125]
	v_cvt_f32_i32_e32 v125, s2
	ds_read_b32 v122, v71 offset:116
	ds_read_b32 v124, v71 offset:148
	v_cndmask_b32_e64 v79, v92, 0, s[24:25]
	v_div_scale_f32 v136, s[2:3], v125, v125, 1.0
	v_rcp_f32_e32 v137, v136
	v_cndmask_b32_e64 v116, v78, v72, s[8:9]
	s_waitcnt lgkmcnt(1)
	v_pk_fma_f32 v[108:109], v[122:123], v[108:109], v[120:121] op_sel_hi:[0,1,1] neg_lo:[1,0,0] neg_hi:[1,0,0]
	v_lshlrev_b32_e32 v78, 16, v79
	v_and_b32_e32 v79, 0xffff0000, v79
	v_pk_fma_f32 v[118:119], v[122:123], v[126:127], v[118:119] op_sel_hi:[0,1,1] neg_lo:[1,0,0] neg_hi:[1,0,0]
	s_waitcnt lgkmcnt(0)
	v_pk_fma_f32 v[126:127], v[124:125], v[78:79], v[108:109] op_sel_hi:[0,1,1]
	v_fma_f32 v108, -v136, v137, 1.0
	v_fmac_f32_e32 v137, v108, v137
	v_div_scale_f32 v108, vcc, 1.0, v125, 1.0
	v_lshlrev_b32_e32 v92, 16, v93
	v_and_b32_e32 v93, 0xffff0000, v93
	v_mul_f32_e32 v109, v108, v137
	v_pk_mul_f32 v[120:121], v[124:125], v[78:79] op_sel_hi:[0,1]
	v_pk_mul_f32 v[122:123], v[124:125], v[92:93] op_sel_hi:[0,1]
	v_pk_fma_f32 v[118:119], v[124:125], v[92:93], v[118:119] op_sel_hi:[0,1,1]
	v_fma_f32 v124, -v136, v109, v108
	v_fmac_f32_e32 v109, v124, v137
	v_fma_f32 v108, -v136, v109, v108
	v_readlane_b32 s2, v252, 0
	v_div_fmas_f32 v108, v108, v137, v109
	s_lshl_b32 s2, s2, 9
	v_div_fixup_f32 v108, v108, v125, 1.0
	s_add_i32 s2, s2, 0
	v_pk_fma_f32 v[122:123], v[108:109], v[118:119], v[122:123] op_sel_hi:[0,1,1] neg_lo:[0,0,1] neg_hi:[0,0,1]
	v_pk_fma_f32 v[108:109], v[108:109], v[126:127], v[120:121] op_sel_hi:[0,1,1] neg_lo:[0,0,1] neg_hi:[0,0,1]
	v_add3_u32 v120, s2, v162, v150
	v_cvt_pk_bf16_f32 v108, v108, v109
	v_cvt_pk_bf16_f32 v109, v122, v123
	ds_write_b64 v120, v[108:109]
	ds_read_b32 v120, v71 offset:120
	s_min_i32 s2, s92, -16
	s_add_i32 s2, s2, 24
	global_load_dwordx2 v[108:109], v[116:117], off
	ds_read_b32 v116, v71 offset:152
	s_waitcnt lgkmcnt(1)
	v_pk_fma_f32 v[118:119], v[120:121], v[130:131], v[118:119] op_sel_hi:[0,1,1] neg_lo:[1,0,0] neg_hi:[1,0,0]
	v_pk_fma_f32 v[120:121], v[120:121], v[106:107], v[126:127] op_sel_hi:[0,1,1] neg_lo:[1,0,0] neg_hi:[1,0,0]
	v_cvt_f32_i32_e32 v126, s2
	v_cndmask_b32_e64 v117, v91, 0, s[22:23]
	v_cndmask_b32_e64 v91, v90, 0, s[22:23]
	v_lshlrev_b32_e32 v90, 16, v91
	v_div_scale_f32 v127, s[2:3], v126, v126, 1.0
	v_rcp_f32_e32 v130, v127
	v_and_b32_e32 v91, 0xffff0000, v91
	v_lshlrev_b32_e32 v106, 16, v117
	v_and_b32_e32 v107, 0xffff0000, v117
	s_waitcnt lgkmcnt(0)
	v_pk_mul_f32 v[122:123], v[116:117], v[90:91] op_sel_hi:[0,1]
	v_pk_mul_f32 v[124:125], v[116:117], v[106:107] op_sel_hi:[0,1]
	v_pk_fma_f32 v[120:121], v[116:117], v[90:91], v[120:121] op_sel_hi:[0,1,1]
	v_pk_fma_f32 v[116:117], v[116:117], v[106:107], v[118:119] op_sel_hi:[0,1,1]
	v_fma_f32 v118, -v127, v130, 1.0
	v_fmac_f32_e32 v130, v118, v130
	v_div_scale_f32 v118, vcc, 1.0, v126, 1.0
	v_mul_f32_e32 v119, v118, v130
	v_fma_f32 v131, -v127, v119, v118
	v_fmac_f32_e32 v119, v131, v130
	v_fma_f32 v118, -v127, v119, v118
	v_readlane_b32 s2, v254, 62
	v_div_fmas_f32 v118, v118, v130, v119
	s_lshl_b32 s2, s2, 9
	v_div_fixup_f32 v118, v118, v126, 1.0
	s_add_i32 s2, s2, 0
	v_pk_fma_f32 v[124:125], v[118:119], v[116:117], v[124:125] op_sel_hi:[0,1,1] neg_lo:[0,0,1] neg_hi:[0,0,1]
	v_pk_fma_f32 v[118:119], v[118:119], v[120:121], v[122:123] op_sel_hi:[0,1,1] neg_lo:[0,0,1] neg_hi:[0,0,1]
	v_add3_u32 v122, s2, v160, v150
	s_min_i32 s2, s92, 0xffffffef
	s_add_i32 s2, s2, 25
	v_cvt_f32_i32_e32 v126, s2
	v_cvt_pk_bf16_f32 v118, v118, v119
	v_cvt_pk_bf16_f32 v119, v124, v125
	ds_write_b64 v122, v[118:119]
	ds_read_b32 v118, v71 offset:124
	v_cndmask_b32_e64 v119, v88, 0, s[20:21]
	ds_read_b32 v88, v71 offset:156
	v_div_scale_f32 v127, s[2:3], v126, v126, 1.0
	v_rcp_f32_e32 v130, v127
	s_waitcnt lgkmcnt(1)
	v_pk_fma_f32 v[116:117], v[118:119], v[134:135], v[116:117] op_sel_hi:[0,1,1] neg_lo:[1,0,0] neg_hi:[1,0,0]
	v_pk_fma_f32 v[104:105], v[118:119], v[104:105], v[120:121] op_sel_hi:[0,1,1] neg_lo:[1,0,0] neg_hi:[1,0,0]
	v_lshlrev_b32_e32 v118, 16, v119
	v_and_b32_e32 v119, 0xffff0000, v119
	v_lshlrev_b32_e32 v120, 16, v89
	v_and_b32_e32 v121, 0xffff0000, v89
	s_waitcnt lgkmcnt(0)
	v_pk_mul_f32 v[122:123], v[88:89], v[118:119] op_sel_hi:[0,1]
	v_pk_mul_f32 v[124:125], v[88:89], v[120:121] op_sel_hi:[0,1]
	v_pk_fma_f32 v[104:105], v[88:89], v[118:119], v[104:105] op_sel_hi:[0,1,1]
	v_pk_fma_f32 v[88:89], v[88:89], v[120:121], v[116:117] op_sel_hi:[0,1,1]
	v_fma_f32 v116, -v127, v130, 1.0
	v_fmac_f32_e32 v130, v116, v130
	v_div_scale_f32 v116, vcc, 1.0, v126, 1.0
	v_mul_f32_e32 v117, v116, v130
	v_fma_f32 v118, -v127, v117, v116
	v_fmac_f32_e32 v117, v118, v130
	v_fma_f32 v116, -v127, v117, v116
	v_div_fmas_f32 v116, v116, v130, v117
	v_readlane_b32 s2, v254, 60
	v_div_fixup_f32 v116, v116, v126, 1.0
	s_lshl_b32 s2, s2, 9
	v_pk_fma_f32 v[118:119], v[116:117], v[88:89], v[124:125] op_sel_hi:[0,1,1] neg_lo:[0,0,1] neg_hi:[0,0,1]
	v_pk_fma_f32 v[116:117], v[116:117], v[104:105], v[122:123] op_sel_hi:[0,1,1] neg_lo:[0,0,1] neg_hi:[0,0,1]
	s_add_i32 s2, s2, 0
	v_cvt_pk_bf16_f32 v116, v116, v117
	v_cvt_pk_bf16_f32 v117, v118, v119
	v_add3_u32 v118, s2, v155, v150
	s_min_i32 s2, s92, 0xffffffee
	s_add_i32 s2, s2, 26
	v_cvt_f32_i32_e32 v122, s2
	ds_write_b64 v118, v[116:117]
	ds_read_b32 v116, v71 offset:128
	v_cndmask_b32_e64 v117, v86, 0, s[18:19]
	ds_read_b32 v86, v71 offset:160
	v_div_scale_f32 v123, s[2:3], v122, v122, 1.0
	v_rcp_f32_e32 v124, v123
	s_waitcnt lgkmcnt(1)
	v_pk_fma_f32 v[88:89], v[116:117], v[132:133], v[88:89] op_sel_hi:[0,1,1] neg_lo:[1,0,0] neg_hi:[1,0,0]
	v_pk_fma_f32 v[102:103], v[116:117], v[102:103], v[104:105] op_sel_hi:[0,1,1] neg_lo:[1,0,0] neg_hi:[1,0,0]
	v_lshlrev_b32_e32 v104, 16, v117
	v_and_b32_e32 v105, 0xffff0000, v117
	v_lshlrev_b32_e32 v116, 16, v87
	v_and_b32_e32 v117, 0xffff0000, v87
	s_waitcnt lgkmcnt(0)
	v_pk_mul_f32 v[118:119], v[86:87], v[104:105] op_sel_hi:[0,1]
	v_pk_mul_f32 v[120:121], v[86:87], v[116:117] op_sel_hi:[0,1]
	v_pk_fma_f32 v[102:103], v[86:87], v[104:105], v[102:103] op_sel_hi:[0,1,1]
	v_pk_fma_f32 v[86:87], v[86:87], v[116:117], v[88:89] op_sel_hi:[0,1,1]
	v_fma_f32 v88, -v123, v124, 1.0
	v_fmac_f32_e32 v124, v88, v124
	v_div_scale_f32 v88, vcc, 1.0, v122, 1.0
	v_mul_f32_e32 v89, v88, v124
	v_fma_f32 v104, -v123, v89, v88
	v_fmac_f32_e32 v89, v104, v124
	v_fma_f32 v88, -v123, v89, v88
	v_div_fmas_f32 v88, v88, v124, v89
	v_readlane_b32 s2, v254, 58
	v_div_fixup_f32 v88, v88, v122, 1.0
	s_lshl_b32 s2, s2, 9
	v_pk_fma_f32 v[104:105], v[88:89], v[86:87], v[120:121] op_sel_hi:[0,1,1] neg_lo:[0,0,1] neg_hi:[0,0,1]
	v_pk_fma_f32 v[88:89], v[88:89], v[102:103], v[118:119] op_sel_hi:[0,1,1] neg_lo:[0,0,1] neg_hi:[0,0,1]
	s_add_i32 s2, s2, 0
	v_cvt_pk_bf16_f32 v88, v88, v89
	v_cvt_pk_bf16_f32 v89, v104, v105
	v_add3_u32 v104, s2, v151, v150
	s_min_i32 s2, s92, 0xffffffed
	s_add_i32 s2, s2, 27
	v_cvt_f32_i32_e32 v118, s2
	ds_write_b64 v104, v[88:89]
	ds_read_b32 v88, v71 offset:132
	v_cndmask_b32_e64 v104, v84, 0, s[16:17]
	ds_read_b32 v84, v71 offset:164
	v_div_scale_f32 v119, s[2:3], v118, v118, 1.0
	v_rcp_f32_e32 v120, v119
	s_waitcnt lgkmcnt(1)
	v_pk_fma_f32 v[86:87], v[88:89], v[128:129], v[86:87] op_sel_hi:[0,1,1] neg_lo:[1,0,0] neg_hi:[1,0,0]
	v_pk_fma_f32 v[88:89], v[88:89], v[100:101], v[102:103] op_sel_hi:[0,1,1] neg_lo:[1,0,0] neg_hi:[1,0,0]
	v_lshlrev_b32_e32 v100, 16, v104
	v_and_b32_e32 v101, 0xffff0000, v104
	v_lshlrev_b32_e32 v102, 16, v85
	v_and_b32_e32 v103, 0xffff0000, v85
	s_waitcnt lgkmcnt(0)
	v_pk_mul_f32 v[104:105], v[84:85], v[100:101] op_sel_hi:[0,1]
	v_pk_mul_f32 v[116:117], v[84:85], v[102:103] op_sel_hi:[0,1]
	v_pk_fma_f32 v[88:89], v[84:85], v[100:101], v[88:89] op_sel_hi:[0,1,1]
	v_pk_fma_f32 v[84:85], v[84:85], v[102:103], v[86:87] op_sel_hi:[0,1,1]
	v_fma_f32 v86, -v119, v120, 1.0
	v_fmac_f32_e32 v120, v86, v120
	v_div_scale_f32 v86, vcc, 1.0, v118, 1.0
	v_mul_f32_e32 v87, v86, v120
	v_fma_f32 v100, -v119, v87, v86
	v_fmac_f32_e32 v87, v100, v120
	v_fma_f32 v86, -v119, v87, v86
	v_div_fmas_f32 v86, v86, v120, v87
	v_readlane_b32 s2, v254, 56
	v_div_fixup_f32 v86, v86, v118, 1.0
	s_lshl_b32 s2, s2, 9
	v_pk_fma_f32 v[100:101], v[86:87], v[84:85], v[116:117] op_sel_hi:[0,1,1] neg_lo:[0,0,1] neg_hi:[0,0,1]
	v_pk_fma_f32 v[86:87], v[86:87], v[88:89], v[104:105] op_sel_hi:[0,1,1] neg_lo:[0,0,1] neg_hi:[0,0,1]
	s_add_i32 s2, s2, 0
	v_cvt_pk_bf16_f32 v86, v86, v87
	v_cvt_pk_bf16_f32 v87, v100, v101
	v_add3_u32 v100, s2, v144, v150
	s_min_i32 s2, s92, 0xffffffec
	ds_write_b64 v100, v[86:87]
	s_add_i32 s2, s2, 28
	v_cndmask_b32_e64 v73, v75, v73, s[10:11]
	v_cndmask_b32_e64 v72, v74, v72, s[10:11]
	ds_read_b32 v86, v71 offset:136
	v_cvt_f32_i32_e32 v105, s2
	global_load_dwordx2 v[72:73], v[72:73], off
	s_waitcnt vmcnt(1)
	v_cndmask_b32_e64 v104, v109, 0, s[8:9]
	v_cndmask_b32_e64 v100, v82, 0, s[14:15]
	ds_read_b32 v82, v71 offset:168
	v_div_scale_f32 v109, s[2:3], v105, v105, 1.0
	s_waitcnt lgkmcnt(1)
	v_pk_fma_f32 v[84:85], v[86:87], v[114:115], v[84:85] op_sel_hi:[0,1,1] neg_lo:[1,0,0] neg_hi:[1,0,0]
	v_rcp_f32_e32 v114, v109
	v_pk_fma_f32 v[86:87], v[86:87], v[98:99], v[88:89] op_sel_hi:[0,1,1] neg_lo:[1,0,0] neg_hi:[1,0,0]
	v_lshlrev_b32_e32 v88, 16, v100
	v_and_b32_e32 v89, 0xffff0000, v100
	v_lshlrev_b32_e32 v98, 16, v83
	v_and_b32_e32 v99, 0xffff0000, v83
	s_waitcnt lgkmcnt(0)
	v_pk_mul_f32 v[100:101], v[82:83], v[88:89] op_sel_hi:[0,1]
	v_pk_mul_f32 v[102:103], v[82:83], v[98:99] op_sel_hi:[0,1]
	v_pk_fma_f32 v[86:87], v[82:83], v[88:89], v[86:87] op_sel_hi:[0,1,1]
	v_pk_fma_f32 v[82:83], v[82:83], v[98:99], v[84:85] op_sel_hi:[0,1,1]
	v_fma_f32 v84, -v109, v114, 1.0
	v_fmac_f32_e32 v114, v84, v114
	v_div_scale_f32 v84, vcc, 1.0, v105, 1.0
	v_mul_f32_e32 v85, v84, v114
	v_fma_f32 v88, -v109, v85, v84
	v_fmac_f32_e32 v85, v88, v114
	v_fma_f32 v84, -v109, v85, v84
	v_div_fmas_f32 v84, v84, v114, v85
	v_readlane_b32 s2, v254, 54
	v_div_fixup_f32 v84, v84, v105, 1.0
	s_lshl_b32 s2, s2, 9
	v_pk_fma_f32 v[88:89], v[84:85], v[82:83], v[102:103] op_sel_hi:[0,1,1] neg_lo:[0,0,1] neg_hi:[0,0,1]
	v_pk_fma_f32 v[84:85], v[84:85], v[86:87], v[100:101] op_sel_hi:[0,1,1] neg_lo:[0,0,1] neg_hi:[0,0,1]
	s_add_i32 s2, s2, 0
	v_cvt_pk_bf16_f32 v84, v84, v85
	v_cvt_pk_bf16_f32 v85, v88, v89
	v_add3_u32 v88, s2, v145, v150
	s_min_i32 s2, s92, 0xffffffeb
	s_add_i32 s2, s2, 29
	v_cvt_f32_i32_e32 v75, s2
	ds_write_b64 v88, v[84:85]
	ds_read_b32 v84, v71 offset:140
	v_cndmask_b32_e64 v88, v80, 0, s[12:13]
	ds_read_b32 v80, v71 offset:172
	v_div_scale_f32 v100, s[2:3], v75, v75, 1.0
	v_rcp_f32_e32 v101, v100
	s_waitcnt lgkmcnt(1)
	v_pk_fma_f32 v[82:83], v[84:85], v[112:113], v[82:83] op_sel_hi:[0,1,1] neg_lo:[1,0,0] neg_hi:[1,0,0]
	v_pk_fma_f32 v[84:85], v[84:85], v[96:97], v[86:87] op_sel_hi:[0,1,1] neg_lo:[1,0,0] neg_hi:[1,0,0]
	v_lshlrev_b32_e32 v86, 16, v88
	v_and_b32_e32 v87, 0xffff0000, v88
	v_lshlrev_b32_e32 v88, 16, v81
	v_and_b32_e32 v89, 0xffff0000, v81
	s_waitcnt lgkmcnt(0)
	v_pk_mul_f32 v[96:97], v[80:81], v[86:87] op_sel_hi:[0,1]
	v_pk_mul_f32 v[98:99], v[80:81], v[88:89] op_sel_hi:[0,1]
	v_pk_fma_f32 v[84:85], v[80:81], v[86:87], v[84:85] op_sel_hi:[0,1,1]
	v_pk_fma_f32 v[80:81], v[80:81], v[88:89], v[82:83] op_sel_hi:[0,1,1]
	v_fma_f32 v82, -v100, v101, 1.0
	v_fmac_f32_e32 v101, v82, v101
	v_div_scale_f32 v82, vcc, 1.0, v75, 1.0
	v_mul_f32_e32 v83, v82, v101
	v_fma_f32 v86, -v100, v83, v82
	v_fmac_f32_e32 v83, v86, v101
	v_readlane_b32 s2, v254, 52
	v_fma_f32 v82, -v100, v83, v82
	s_lshl_b32 s2, s2, 9
	v_div_fmas_f32 v82, v82, v101, v83
	s_add_i32 s2, s2, 0
	v_div_fixup_f32 v82, v82, v75, 1.0
	v_add3_u32 v75, s2, v146, v150
	s_min_i32 s2, s92, 0xffffffea
	s_add_i32 s2, s2, 30
	v_pk_fma_f32 v[86:87], v[82:83], v[80:81], v[98:99] op_sel_hi:[0,1,1] neg_lo:[0,0,1] neg_hi:[0,0,1]
	v_pk_fma_f32 v[82:83], v[82:83], v[84:85], v[96:97] op_sel_hi:[0,1,1] neg_lo:[0,0,1] neg_hi:[0,0,1]
	v_cvt_f32_i32_e32 v96, s2
	v_cvt_pk_bf16_f32 v82, v82, v83
	v_cvt_pk_bf16_f32 v83, v86, v87
	ds_write_b64 v75, v[82:83]
	ds_read_b32 v82, v71 offset:144
	ds_read_b32 v74, v71 offset:176
	v_div_scale_f32 v97, s[2:3], v96, v96, 1.0
	v_rcp_f32_e32 v98, v97
	v_cndmask_b32_e64 v75, v108, 0, s[8:9]
	s_waitcnt lgkmcnt(1)
	v_pk_fma_f32 v[80:81], v[82:83], v[110:111], v[80:81] op_sel_hi:[0,1,1] neg_lo:[1,0,0] neg_hi:[1,0,0]
	v_pk_fma_f32 v[82:83], v[82:83], v[94:95], v[84:85] op_sel_hi:[0,1,1] neg_lo:[1,0,0] neg_hi:[1,0,0]
	v_lshlrev_b32_e32 v84, 16, v75
	v_and_b32_e32 v85, 0xffff0000, v75
	v_lshlrev_b32_e32 v86, 16, v104
	v_and_b32_e32 v87, 0xffff0000, v104
	s_waitcnt lgkmcnt(0)
	v_pk_mul_f32 v[88:89], v[74:75], v[84:85] op_sel_hi:[0,1]
	v_pk_mul_f32 v[94:95], v[74:75], v[86:87] op_sel_hi:[0,1]
	v_pk_fma_f32 v[82:83], v[74:75], v[84:85], v[82:83] op_sel_hi:[0,1,1]
	v_pk_fma_f32 v[74:75], v[74:75], v[86:87], v[80:81] op_sel_hi:[0,1,1]
	v_fma_f32 v80, -v97, v98, 1.0
	v_fmac_f32_e32 v98, v80, v98
	v_div_scale_f32 v80, vcc, 1.0, v96, 1.0
	v_mul_f32_e32 v81, v80, v98
	v_fma_f32 v84, -v97, v81, v80
	v_fmac_f32_e32 v81, v84, v98
	v_fma_f32 v80, -v97, v81, v80
	v_div_fmas_f32 v80, v80, v98, v81
	v_readlane_b32 s2, v254, 50
	v_div_fixup_f32 v80, v80, v96, 1.0
	s_lshl_b32 s2, s2, 9
	v_pk_fma_f32 v[84:85], v[80:81], v[74:75], v[94:95] op_sel_hi:[0,1,1] neg_lo:[0,0,1] neg_hi:[0,0,1]
	v_pk_fma_f32 v[80:81], v[80:81], v[82:83], v[88:89] op_sel_hi:[0,1,1] neg_lo:[0,0,1] neg_hi:[0,0,1]
	s_add_i32 s2, s2, 0
	v_cvt_pk_bf16_f32 v80, v80, v81
	v_cvt_pk_bf16_f32 v81, v84, v85
	v_add3_u32 v84, s2, v142, v150
	ds_write_b64 v84, v[80:81]
	ds_read_b32 v80, v71 offset:148
	s_min_i32 s2, s92, 0xffffffe9
	v_cndmask_b32_e64 v81, v76, 0, s[6:7]
	ds_read_b32 v76, v71 offset:180
	s_add_i32 s2, s2, 31
	v_cvt_f32_i32_e32 v88, s2
	s_waitcnt lgkmcnt(1)
	v_pk_fma_f32 v[74:75], v[80:81], v[92:93], v[74:75] op_sel_hi:[0,1,1] neg_lo:[1,0,0] neg_hi:[1,0,0]
	v_pk_fma_f32 v[78:79], v[80:81], v[78:79], v[82:83] op_sel_hi:[0,1,1] neg_lo:[1,0,0] neg_hi:[1,0,0]
	v_lshlrev_b32_e32 v80, 16, v81
	v_and_b32_e32 v81, 0xffff0000, v81
	v_lshlrev_b32_e32 v82, 16, v77
	v_and_b32_e32 v83, 0xffff0000, v77
	s_waitcnt lgkmcnt(0)
	v_pk_mul_f32 v[84:85], v[76:77], v[80:81] op_sel_hi:[0,1]
	v_div_scale_f32 v77, s[2:3], v88, v88, 1.0
	v_rcp_f32_e32 v89, v77
	v_pk_mul_f32 v[86:87], v[76:77], v[82:83] op_sel_hi:[0,1]
	v_pk_fma_f32 v[78:79], v[76:77], v[80:81], v[78:79] op_sel_hi:[0,1,1]
	v_pk_fma_f32 v[74:75], v[76:77], v[82:83], v[74:75] op_sel_hi:[0,1,1]
	v_fma_f32 v76, -v77, v89, 1.0
	v_fmac_f32_e32 v89, v76, v89
	v_div_scale_f32 v76, vcc, 1.0, v88, 1.0
	v_mul_f32_e32 v80, v76, v89
	v_fma_f32 v81, -v77, v80, v76
	v_fmac_f32_e32 v80, v81, v89
	v_fma_f32 v76, -v77, v80, v76
	v_div_fmas_f32 v76, v76, v89, v80
	v_readlane_b32 s2, v254, 49
	v_div_fixup_f32 v76, v76, v88, 1.0
	s_lshl_b32 s2, s2, 9
	v_pk_fma_f32 v[80:81], v[76:77], v[74:75], v[86:87] op_sel_hi:[0,1,1] neg_lo:[0,0,1] neg_hi:[0,0,1]
	v_pk_fma_f32 v[76:77], v[76:77], v[78:79], v[84:85] op_sel_hi:[0,1,1] neg_lo:[0,0,1] neg_hi:[0,0,1]
	s_add_i32 s2, s2, 0
	v_cvt_pk_bf16_f32 v76, v76, v77
	v_cvt_pk_bf16_f32 v77, v80, v81
	v_add3_u32 v80, s2, v140, v150
	s_min_i32 s2, s92, 0xffffffe8
	ds_write_b64 v80, v[76:77]
	s_add_i32 s2, s2, 32
	ds_read_b32 v76, v71 offset:152
	s_waitcnt vmcnt(0)
	v_cndmask_b32_e64 v80, v72, 0, s[10:11]
	ds_read_b32 v72, v71 offset:184
	v_cvt_f32_i32_e32 v71, s2
	v_cndmask_b32_e64 v73, v73, 0, s[10:11]
	s_waitcnt lgkmcnt(1)
	v_pk_fma_f32 v[74:75], v[76:77], v[106:107], v[74:75] op_sel_hi:[0,1,1] neg_lo:[1,0,0] neg_hi:[1,0,0]
	v_pk_fma_f32 v[76:77], v[76:77], v[90:91], v[78:79] op_sel_hi:[0,1,1] neg_lo:[1,0,0] neg_hi:[1,0,0]
	v_div_scale_f32 v86, s[2:3], v71, v71, 1.0
	v_rcp_f32_e32 v87, v86
	v_lshlrev_b32_e32 v78, 16, v80
	v_and_b32_e32 v79, 0xffff0000, v80
	v_lshlrev_b32_e32 v80, 16, v73
	v_and_b32_e32 v81, 0xffff0000, v73
	s_waitcnt lgkmcnt(0)
	v_pk_mul_f32 v[82:83], v[72:73], v[78:79] op_sel_hi:[0,1]
	v_pk_mul_f32 v[84:85], v[72:73], v[80:81] op_sel_hi:[0,1]
	v_pk_fma_f32 v[76:77], v[72:73], v[78:79], v[76:77] op_sel_hi:[0,1,1]
	v_pk_fma_f32 v[72:73], v[72:73], v[80:81], v[74:75] op_sel_hi:[0,1,1]
	v_fma_f32 v74, -v86, v87, 1.0
	v_fmac_f32_e32 v87, v74, v87
	v_div_scale_f32 v74, vcc, 1.0, v71, 1.0
	v_mul_f32_e32 v75, v74, v87
	v_fma_f32 v78, -v86, v75, v74
	v_fmac_f32_e32 v75, v78, v87
	v_fma_f32 v74, -v86, v75, v74
	v_div_fmas_f32 v74, v74, v87, v75
	v_div_fixup_f32 v74, v74, v71, 1.0
	v_readlane_b32 s38, v252, 7
	v_pk_fma_f32 v[78:79], v[74:75], v[72:73], v[84:85] op_sel_hi:[0,1,1] neg_lo:[0,0,1] neg_hi:[0,0,1]
	v_pk_fma_f32 v[72:73], v[74:75], v[76:77], v[82:83] op_sel_hi:[0,1,1] neg_lo:[0,0,1] neg_hi:[0,0,1]
	v_readlane_b32 s2, v254, 48
	v_readlane_b32 s6, v254, 6
	v_readlane_b32 s42, v254, 20
	v_readlane_b32 s50, v254, 31
	v_readlane_b32 s39, v252, 8
	s_mov_b32 s18, s86
	s_mov_b32 s16, s92
	v_cvt_pk_bf16_f32 v72, v72, v73
	v_cvt_pk_bf16_f32 v73, v78, v79
	v_mov_b32_e32 v74, s2
	v_readlane_b32 s7, v254, 7
	v_readlane_b32 s92, v254, 9
	v_readlane_b32 s95, v254, 12
	v_readlane_b32 s43, v254, 21
	v_readlane_b32 s41, v254, 25
	s_mov_b32 s44, 0xf800000
	s_movk_i32 s12, 0x1ff
	v_readlane_b32 s46, v254, 30
	v_readlane_b32 s51, v254, 32
	v_readlane_b32 s15, v254, 46
	s_mov_b64 s[8:9], 0
